# GEMM K-loops: LDS-DMA addressed as SGPR base + 32-bit VGPR offset (16 fewer 64-bit VALU adds per iteration)
# speedup vs baseline: 1.0039x; 1.0026x over previous
; #define PG8_STAGE(bufoff, gbase, voff) do { _Pragma("unroll") for (int _i = 0; _i < 2; ++_i) \
;         __builtin_amdgcn_global_load_lds((const unsigned*)((const char*)(gbase) + (voff)[_i]), (LAS unsigned*)(lds + (bufoff) + ldsw + _i * 8192), 16, 0, 0); } while (0)
; #define PG8_LDA(dst, b, h) do { _Pragma("unroll") for (int m = 0; m < 4; ++m) _Pragma("unroll") for (int k = 0; k < 2; ++k) dst[m][k] = *(const LAS bf16x8*)(lds + PG8_SA(b, h) + aoff + m * 2048 + k * 1024); } while (0)
; #define PG8_LDB(dst, b, h) do { _Pragma("unroll") for (int n = 0; n < 2; ++n) _Pragma("unroll") for (int k = 0; k < 2; ++k) dst[n][k] = *(const LAS bf16x8*)(lds + PG8_SB(b, h) + boff + n * 2048 + k * 1024); } while (0)
; #define PG8_MMA(ai, bj, At, Bt) do { __builtin_amdgcn_s_setprio(1); _Pragma("unroll") for (int m = 0; m < 4; ++m) _Pragma("unroll") for (int n = 0; n < 2; ++n) _Pragma("unroll") for (int k = 0; k < 2; ++k) \
;         acc[ai][bj][m][n] = __builtin_amdgcn_mfma_f32_16x16x32_bf16(Bt[n][k], At[m][k], acc[ai][bj][m][n], 0, 0, 0); __builtin_amdgcn_s_setprio(0); } while (0)
; #define PG8_WAIT_V(n) asm volatile("s_waitcnt vmcnt(" #n ")" ::: "memory")
; #define PG8_WAIT_L(n) asm volatile("s_waitcnt lgkmcnt(" #n ")" ::: "memory")
; #define PG8_BAR __builtin_amdgcn_s_barrier()
; template <class Epi, class Sched>
; __device__ __forceinline__ void gemm_phase(LAS unsigned char* lds, const Gemm g, const Sched& S, const Epi& E) {
;     ...
;         for (int t = 0; t < nt; t += 2) {
;             const bool last = (t == nt - 2);
;             const char* a1 = cA + (size_t)(t + 1) * kstep;
;             const char* a2 = last ? nA : cA + (size_t)(t + 2) * kstep; const char* b2 = last ? nB : cB + (size_t)(t + 2) * kstep;
;             const char* a3 = a2 + kstep; const char* b3 = b2 + kstep;
;             if (last && has_next) S.a_ready(nxt);
;             PG8_LDB(B0, 0, 0); PG8_LDB(B1, 0, 1); PG8_SCHED; PG8_LDA(At, 0, 0); PG8_STAGE(PG8_SA(1, 1), a1 + hstep, voffA);
;             PG8_WAIT_V(8); PG8_WAIT_L(0); PG8_BAR; PG8_MMA(0, 0, At, B0); PG8_MMA(0, 1, At, B1); PG8_BAR; PG8_SCHED;
;             PG8_LDA(At, 0, 1); PG8_STAGE(PG8_SB(0, 0), b2, voffB); PG8_STAGE(PG8_SB(0, 1), b2 + hstep, voffB); PG8_STAGE(PG8_SA(0, 0), a2, voffA);
;             PG8_WAIT_V(8); PG8_WAIT_L(0); PG8_BAR; PG8_MMA(1, 0, At, B0); PG8_MMA(1, 1, At, B1); PG8_BAR; PG8_SCHED;
.LBB0_131:
	s_add_i32 s58, s50, 2
	s_add_u32 s48, s46, 0x100
	s_addc_u32 s49, s47, 0
	s_add_u32 s1, s9, s46
	s_addc_u32 s51, s36, s47
	s_cmp_eq_u32 s56, s50
	s_cselect_b32 s50, 0, s48
	s_cselect_b32 s59, 0, s49
	s_cselect_b32 s60, s44, s1
	s_cselect_b32 s61, s45, s51
	s_add_u32 s50, s2, s50
	s_addc_u32 s51, s3, s59
	s_add_i32 s1, 0, 0x10000
	s_add_i32 s59, 0, 0x14000
	v_add_u32_e32 v156, s1, v142
	v_add_u32_e32 v172, s59, v142
	ds_read_b128 v[144:147], v156
	ds_read_b128 v[148:151], v156 offset:1024
	ds_read_b128 v[152:155], v156 offset:2048
	ds_read_b128 v[156:159], v156 offset:3072
	ds_read_b128 v[160:163], v172
	ds_read_b128 v[164:167], v172 offset:1024
	ds_read_b128 v[168:171], v172 offset:2048
	ds_read_b128 v[172:175], v172 offset:3072
	s_add_u32 s46, s46, s2
	s_addc_u32 s47, s47, s3
	s_add_u32 s46, s46, s20
	s_addc_u32 s47, s47, s21
	s_add_u32 s46, s46, 0x80
	s_addc_u32 s47, s47, 0
	s_add_i32 m0, s5, 0xc000
	ds_read_b128 v[176:179], v143
	ds_read_b128 v[180:183], v143 offset:1024
	ds_read_b128 v[184:187], v143 offset:2048
	ds_read_b128 v[192:195], v143 offset:3072
	ds_read_b128 v[196:199], v143 offset:4096
	ds_read_b128 v[200:203], v143 offset:5120
	ds_read_b128 v[204:207], v143 offset:6144
	ds_read_b128 v[208:211], v143 offset:7168
	global_load_lds_dwordx4 v134, s[46:47]
	s_add_i32 m0, s5, 0xe000
	s_nop 0
	global_load_lds_dwordx4 v132, s[46:47]
	s_waitcnt vmcnt(8)
	s_waitcnt lgkmcnt(0)
	s_barrier
	s_setprio 1
	s_waitcnt lgkmcnt(0)
	v_mfma_f32_16x16x32_bf16 v[122:125], v[144:147], v[176:179], v[122:125]
	v_mfma_f32_16x16x32_bf16 v[126:129], v[152:155], v[176:179], v[126:129]
	v_mfma_f32_16x16x32_bf16 v[110:113], v[144:147], v[184:187], v[110:113]
	v_mfma_f32_16x16x32_bf16 v[106:109], v[152:155], v[184:187], v[106:109]
	v_mfma_f32_16x16x32_bf16 v[94:97], v[144:147], v[196:199], v[94:97]
	v_mfma_f32_16x16x32_bf16 v[90:93], v[152:155], v[196:199], v[90:93]
	v_mfma_f32_16x16x32_bf16 v[78:81], v[144:147], v[204:207], v[78:81]
	v_mfma_f32_16x16x32_bf16 v[74:77], v[152:155], v[204:207], v[74:77]
	v_mfma_f32_16x16x32_bf16 v[122:125], v[148:151], v[180:183], v[122:125]
	v_mfma_f32_16x16x32_bf16 v[126:129], v[156:159], v[180:183], v[126:129]
	v_mfma_f32_16x16x32_bf16 v[110:113], v[148:151], v[192:195], v[110:113]
	v_mfma_f32_16x16x32_bf16 v[106:109], v[156:159], v[192:195], v[106:109]
	v_mfma_f32_16x16x32_bf16 v[94:97], v[148:151], v[200:203], v[94:97]
	v_mfma_f32_16x16x32_bf16 v[90:93], v[156:159], v[200:203], v[90:93]
	v_mfma_f32_16x16x32_bf16 v[78:81], v[148:151], v[208:211], v[78:81]
	v_mfma_f32_16x16x32_bf16 v[74:77], v[156:159], v[208:211], v[74:77]
	s_setprio 0
	s_setprio 1
	v_mfma_f32_16x16x32_bf16 v[118:121], v[160:163], v[176:179], v[118:121]
	v_mfma_f32_16x16x32_bf16 v[114:117], v[168:171], v[176:179], v[114:117]
	v_mfma_f32_16x16x32_bf16 v[102:105], v[160:163], v[184:187], v[102:105]
	v_mfma_f32_16x16x32_bf16 v[98:101], v[168:171], v[184:187], v[98:101]
	v_mfma_f32_16x16x32_bf16 v[86:89], v[160:163], v[196:199], v[86:89]
	v_mfma_f32_16x16x32_bf16 v[82:85], v[168:171], v[196:199], v[82:85]
	v_mfma_f32_16x16x32_bf16 v[70:73], v[160:163], v[204:207], v[70:73]
	v_mfma_f32_16x16x32_bf16 v[66:69], v[168:171], v[204:207], v[66:69]
	v_mfma_f32_16x16x32_bf16 v[118:121], v[164:167], v[180:183], v[118:121]
	v_mfma_f32_16x16x32_bf16 v[114:117], v[172:175], v[180:183], v[114:117]
	v_mfma_f32_16x16x32_bf16 v[102:105], v[164:167], v[192:195], v[102:105]
	v_mfma_f32_16x16x32_bf16 v[98:101], v[172:175], v[192:195], v[98:101]
	v_mfma_f32_16x16x32_bf16 v[86:89], v[164:167], v[200:203], v[86:89]
	v_mfma_f32_16x16x32_bf16 v[82:85], v[172:175], v[200:203], v[82:85]
	v_mfma_f32_16x16x32_bf16 v[70:73], v[164:167], v[208:211], v[70:73]
	v_mfma_f32_16x16x32_bf16 v[66:69], v[172:175], v[208:211], v[66:69]
	s_setprio 0
	s_barrier
	s_add_i32 s1, s1, s4
	s_mov_b32 m0, s1
	ds_read_b128 v[176:179], v143 offset:16384
	ds_read_b128 v[180:183], v143 offset:17408
	ds_read_b128 v[184:187], v143 offset:18432
	ds_read_b128 v[192:195], v143 offset:19456
	ds_read_b128 v[196:199], v143 offset:20480
	ds_read_b128 v[200:203], v143 offset:21504
	ds_read_b128 v[204:207], v143 offset:22528
	ds_read_b128 v[208:211], v143 offset:23552
	global_load_lds_dwordx4 v0, s[60:61]
	s_add_i32 m0, s1, 0x2000
	s_add_u32 s46, s60, s20
	s_addc_u32 s47, s61, s21
	s_add_i32 s1, s59, s4
	global_load_lds_dwordx4 v130, s[60:61]
	s_mov_b32 m0, s1
	s_nop 0
	global_load_lds_dwordx4 v0, s[46:47]
	s_add_i32 m0, s1, 0x2000
	s_nop 0
	global_load_lds_dwordx4 v130, s[46:47]
	s_mov_b32 m0, s5
	s_nop 0
	global_load_lds_dwordx4 v134, s[50:51]
	s_mov_b32 m0, s18
	s_nop 0
	global_load_lds_dwordx4 v132, s[50:51]
	s_waitcnt vmcnt(8)
	s_waitcnt lgkmcnt(0)
	s_barrier
; #define PG8_STAGE(bufoff, gbase, voff) do { _Pragma("unroll") for (int _i = 0; _i < 2; ++_i) \
;         __builtin_amdgcn_global_load_lds((const unsigned*)((const char*)(gbase) + (voff)[_i]), (LAS unsigned*)(lds + (bufoff) + ldsw + _i * 8192), 16, 0, 0); } while (0)
; #define PG8_LDA(dst, b, h) do { _Pragma("unroll") for (int m = 0; m < 4; ++m) _Pragma("unroll") for (int k = 0; k < 2; ++k) dst[m][k] = *(const LAS bf16x8*)(lds + PG8_SA(b, h) + aoff + m * 2048 + k * 1024); } while (0)
; #define PG8_LDB(dst, b, h) do { _Pragma("unroll") for (int n = 0; n < 2; ++n) _Pragma("unroll") for (int k = 0; k < 2; ++k) dst[n][k] = *(const LAS bf16x8*)(lds + PG8_SB(b, h) + boff + n * 2048 + k * 1024); } while (0)
; #define PG8_MMA(ai, bj, At, Bt) do { __builtin_amdgcn_s_setprio(1); _Pragma("unroll") for (int m = 0; m < 4; ++m) _Pragma("unroll") for (int n = 0; n < 2; ++n) _Pragma("unroll") for (int k = 0; k < 2; ++k) \
;         acc[ai][bj][m][n] = __builtin_amdgcn_mfma_f32_16x16x32_bf16(Bt[n][k], At[m][k], acc[ai][bj][m][n], 0, 0, 0); __builtin_amdgcn_s_setprio(0); } while (0)
; #define PG8_WAIT_V(n) asm volatile("s_waitcnt vmcnt(" #n ")" ::: "memory")
; #define PG8_WAIT_L(n) asm volatile("s_waitcnt lgkmcnt(" #n ")" ::: "memory")
; #define PG8_BAR __builtin_amdgcn_s_barrier()
; #define PG8_SCHED __builtin_amdgcn_sched_barrier(0)
; template <class Epi, class Sched>
; __device__ __forceinline__ void gemm_phase(LAS unsigned char* lds, const Gemm g, const Sched& S, const Epi& E) {
;     ...
;             PG8_WAIT_V(8); PG8_WAIT_L(0); PG8_BAR; PG8_MMA(1, 0, At, B0); PG8_MMA(1, 1, At, B1); PG8_BAR; PG8_SCHED;
;             PG8_LDB(B0, 1, 0); PG8_LDB(B1, 1, 1); PG8_SCHED; PG8_LDA(At, 1, 0); PG8_STAGE(PG8_SA(0, 1), a2 + hstep, voffA);
;             PG8_WAIT_V(8); PG8_WAIT_L(0); PG8_BAR; PG8_MMA(0, 0, At, B0); PG8_MMA(0, 1, At, B1); PG8_BAR; PG8_SCHED;
	s_setprio 1
	s_waitcnt lgkmcnt(0)
	v_mfma_f32_16x16x32_bf16 v[62:65], v[144:147], v[176:179], v[62:65]
	v_mfma_f32_16x16x32_bf16 v[58:61], v[152:155], v[176:179], v[58:61]
	v_mfma_f32_16x16x32_bf16 v[46:49], v[144:147], v[184:187], v[46:49]
	v_mfma_f32_16x16x32_bf16 v[42:45], v[152:155], v[184:187], v[42:45]
	v_mfma_f32_16x16x32_bf16 v[30:33], v[144:147], v[196:199], v[30:33]
	v_mfma_f32_16x16x32_bf16 v[26:29], v[152:155], v[196:199], v[26:29]
	v_mfma_f32_16x16x32_bf16 v[14:17], v[144:147], v[204:207], v[14:17]
	v_mfma_f32_16x16x32_bf16 v[10:13], v[152:155], v[204:207], v[10:13]
	v_mfma_f32_16x16x32_bf16 v[62:65], v[148:151], v[180:183], v[62:65]
	v_mfma_f32_16x16x32_bf16 v[58:61], v[156:159], v[180:183], v[58:61]
	v_mfma_f32_16x16x32_bf16 v[46:49], v[148:151], v[192:195], v[46:49]
	v_mfma_f32_16x16x32_bf16 v[42:45], v[156:159], v[192:195], v[42:45]
	v_mfma_f32_16x16x32_bf16 v[30:33], v[148:151], v[200:203], v[30:33]
	v_mfma_f32_16x16x32_bf16 v[26:29], v[156:159], v[200:203], v[26:29]
	v_mfma_f32_16x16x32_bf16 v[14:17], v[148:151], v[208:211], v[14:17]
	v_mfma_f32_16x16x32_bf16 v[10:13], v[156:159], v[208:211], v[10:13]
	s_setprio 0
	s_setprio 1
	v_mfma_f32_16x16x32_bf16 v[54:57], v[160:163], v[176:179], v[54:57]
	v_mfma_f32_16x16x32_bf16 v[50:53], v[168:171], v[176:179], v[50:53]
	v_mfma_f32_16x16x32_bf16 v[38:41], v[160:163], v[184:187], v[38:41]
	v_mfma_f32_16x16x32_bf16 v[34:37], v[168:171], v[184:187], v[34:37]
	v_mfma_f32_16x16x32_bf16 v[22:25], v[160:163], v[196:199], v[22:25]
	v_mfma_f32_16x16x32_bf16 v[18:21], v[168:171], v[196:199], v[18:21]
	v_mfma_f32_16x16x32_bf16 v[6:9], v[160:163], v[204:207], v[6:9]
	v_mfma_f32_16x16x32_bf16 v[2:5], v[168:171], v[204:207], v[2:5]
	v_mfma_f32_16x16x32_bf16 v[54:57], v[164:167], v[180:183], v[54:57]
	v_mfma_f32_16x16x32_bf16 v[50:53], v[172:175], v[180:183], v[50:53]
	v_mfma_f32_16x16x32_bf16 v[38:41], v[164:167], v[192:195], v[38:41]
	v_mfma_f32_16x16x32_bf16 v[34:37], v[172:175], v[192:195], v[34:37]
	v_mfma_f32_16x16x32_bf16 v[22:25], v[164:167], v[200:203], v[22:25]
	v_mfma_f32_16x16x32_bf16 v[18:21], v[172:175], v[200:203], v[18:21]
	v_mfma_f32_16x16x32_bf16 v[6:9], v[164:167], v[208:211], v[6:9]
	v_mfma_f32_16x16x32_bf16 v[2:5], v[172:175], v[208:211], v[2:5]
	s_setprio 0
	s_barrier
	s_add_i32 s1, 0, 0x18000
	s_add_i32 s59, 0, 0x1c000
	v_add_u32_e32 v156, s1, v142
	v_add_u32_e32 v172, s59, v142
	ds_read_b128 v[144:147], v156
	ds_read_b128 v[148:151], v156 offset:1024
	ds_read_b128 v[152:155], v156 offset:2048
	ds_read_b128 v[156:159], v156 offset:3072
	ds_read_b128 v[160:163], v172
	ds_read_b128 v[164:167], v172 offset:1024
	ds_read_b128 v[168:171], v172 offset:2048
	ds_read_b128 v[172:175], v172 offset:3072
	s_add_u32 s46, s50, s20
	s_addc_u32 s47, s51, s21
	s_mov_b32 m0, s19
	ds_read_b128 v[176:179], v143 offset:32768
	ds_read_b128 v[180:183], v143 offset:33792
	ds_read_b128 v[184:187], v143 offset:34816
	ds_read_b128 v[192:195], v143 offset:35840
	ds_read_b128 v[196:199], v143 offset:36864
	ds_read_b128 v[200:203], v143 offset:37888
	ds_read_b128 v[204:207], v143 offset:38912
	ds_read_b128 v[208:211], v143 offset:39936
	global_load_lds_dwordx4 v134, s[46:47]
	s_mov_b32 m0, s52
	s_nop 0
	global_load_lds_dwordx4 v132, s[46:47]
	s_waitcnt vmcnt(8)
	s_waitcnt lgkmcnt(0)
	s_barrier
	s_setprio 1
	s_waitcnt lgkmcnt(0)
	v_mfma_f32_16x16x32_bf16 v[122:125], v[144:147], v[176:179], v[122:125]
	v_mfma_f32_16x16x32_bf16 v[126:129], v[152:155], v[176:179], v[126:129]
	v_mfma_f32_16x16x32_bf16 v[110:113], v[144:147], v[184:187], v[110:113]
	v_mfma_f32_16x16x32_bf16 v[106:109], v[152:155], v[184:187], v[106:109]
	v_mfma_f32_16x16x32_bf16 v[94:97], v[144:147], v[196:199], v[94:97]
	v_mfma_f32_16x16x32_bf16 v[90:93], v[152:155], v[196:199], v[90:93]
	v_mfma_f32_16x16x32_bf16 v[78:81], v[144:147], v[204:207], v[78:81]
	v_mfma_f32_16x16x32_bf16 v[74:77], v[152:155], v[204:207], v[74:77]
	v_mfma_f32_16x16x32_bf16 v[122:125], v[148:151], v[180:183], v[122:125]
	v_mfma_f32_16x16x32_bf16 v[126:129], v[156:159], v[180:183], v[126:129]
	v_mfma_f32_16x16x32_bf16 v[110:113], v[148:151], v[192:195], v[110:113]
	v_mfma_f32_16x16x32_bf16 v[106:109], v[156:159], v[192:195], v[106:109]
	v_mfma_f32_16x16x32_bf16 v[94:97], v[148:151], v[200:203], v[94:97]
	v_mfma_f32_16x16x32_bf16 v[90:93], v[156:159], v[200:203], v[90:93]
	v_mfma_f32_16x16x32_bf16 v[78:81], v[148:151], v[208:211], v[78:81]
	v_mfma_f32_16x16x32_bf16 v[74:77], v[156:159], v[208:211], v[74:77]
	s_setprio 0
	s_setprio 1
	v_mfma_f32_16x16x32_bf16 v[118:121], v[160:163], v[176:179], v[118:121]
	v_mfma_f32_16x16x32_bf16 v[114:117], v[168:171], v[176:179], v[114:117]
	v_mfma_f32_16x16x32_bf16 v[102:105], v[160:163], v[184:187], v[102:105]
	v_mfma_f32_16x16x32_bf16 v[98:101], v[168:171], v[184:187], v[98:101]
	v_mfma_f32_16x16x32_bf16 v[86:89], v[160:163], v[196:199], v[86:89]
	v_mfma_f32_16x16x32_bf16 v[82:85], v[168:171], v[196:199], v[82:85]
	v_mfma_f32_16x16x32_bf16 v[70:73], v[160:163], v[204:207], v[70:73]
	v_mfma_f32_16x16x32_bf16 v[66:69], v[168:171], v[204:207], v[66:69]
	v_mfma_f32_16x16x32_bf16 v[118:121], v[164:167], v[180:183], v[118:121]
	v_mfma_f32_16x16x32_bf16 v[114:117], v[172:175], v[180:183], v[114:117]
	v_mfma_f32_16x16x32_bf16 v[102:105], v[164:167], v[192:195], v[102:105]
	v_mfma_f32_16x16x32_bf16 v[98:101], v[172:175], v[192:195], v[98:101]
	v_mfma_f32_16x16x32_bf16 v[86:89], v[164:167], v[200:203], v[86:89]
	v_mfma_f32_16x16x32_bf16 v[82:85], v[172:175], v[200:203], v[82:85]
	v_mfma_f32_16x16x32_bf16 v[70:73], v[164:167], v[208:211], v[70:73]
	v_mfma_f32_16x16x32_bf16 v[66:69], v[172:175], v[208:211], v[66:69]
	s_setprio 0
	s_barrier
; #define PG8_STAGE(bufoff, gbase, voff) do { _Pragma("unroll") for (int _i = 0; _i < 2; ++_i) \
;         __builtin_amdgcn_global_load_lds((const unsigned*)((const char*)(gbase) + (voff)[_i]), (LAS unsigned*)(lds + (bufoff) + ldsw + _i * 8192), 16, 0, 0); } while (0)
; #define PG8_LDA(dst, b, h) do { _Pragma("unroll") for (int m = 0; m < 4; ++m) _Pragma("unroll") for (int k = 0; k < 2; ++k) dst[m][k] = *(const LAS bf16x8*)(lds + PG8_SA(b, h) + aoff + m * 2048 + k * 1024); } while (0)
; #define PG8_MMA(ai, bj, At, Bt) do { __builtin_amdgcn_s_setprio(1); _Pragma("unroll") for (int m = 0; m < 4; ++m) _Pragma("unroll") for (int n = 0; n < 2; ++n) _Pragma("unroll") for (int k = 0; k < 2; ++k) \
;         acc[ai][bj][m][n] = __builtin_amdgcn_mfma_f32_16x16x32_bf16(Bt[n][k], At[m][k], acc[ai][bj][m][n], 0, 0, 0); __builtin_amdgcn_s_setprio(0); } while (0)
; #define PG8_WAIT_V(n) asm volatile("s_waitcnt vmcnt(" #n ")" ::: "memory")
; #define PG8_WAIT_L(n) asm volatile("s_waitcnt lgkmcnt(" #n ")" ::: "memory")
; #define PG8_BAR __builtin_amdgcn_s_barrier()
; #define PG8_SCHED __builtin_amdgcn_sched_barrier(0)
; template <class Epi, class Sched>
; __device__ __forceinline__ void gemm_phase(LAS unsigned char* lds, const Gemm g, const Sched& S, const Epi& E) {
;     ...
;             PG8_LDA(At, 1, 1); PG8_STAGE(PG8_SB(1, 0), b3, voffB); PG8_STAGE(PG8_SB(1, 1), b3 + hstep, voffB); PG8_STAGE(PG8_SA(1, 0), a3, voffA);
;             PG8_WAIT_V(8); PG8_WAIT_L(0); PG8_BAR; PG8_MMA(1, 0, At, B0); PG8_MMA(1, 1, At, B1); PG8_BAR; PG8_SCHED;
;         }
	s_add_i32 s1, s1, s4
	s_add_u32 s46, s60, 0x80
	s_addc_u32 s47, s61, 0
	s_mov_b32 m0, s1
	ds_read_b128 v[176:179], v143 offset:49152
	ds_read_b128 v[180:183], v143 offset:50176
	ds_read_b128 v[184:187], v143 offset:51200
	ds_read_b128 v[192:195], v143 offset:52224
	ds_read_b128 v[196:199], v143 offset:53248
	ds_read_b128 v[200:203], v143 offset:54272
	ds_read_b128 v[204:207], v143 offset:55296
	ds_read_b128 v[208:211], v143 offset:56320
	global_load_lds_dwordx4 v0, s[46:47]
	s_add_i32 m0, s1, 0x2000
	s_add_i32 s1, s59, s4
	global_load_lds_dwordx4 v130, s[46:47]
	s_add_u32 s46, s46, s20
	s_addc_u32 s47, s47, s21
	s_mov_b32 m0, s1
	s_nop 0
	global_load_lds_dwordx4 v0, s[46:47]
	s_add_i32 m0, s1, 0x2000
	s_nop 0
	global_load_lds_dwordx4 v130, s[46:47]
	s_add_u32 s46, s50, 0x80
	s_addc_u32 s47, s51, 0
	s_mov_b32 m0, s53
	s_nop 0
	global_load_lds_dwordx4 v134, s[46:47]
	s_mov_b32 m0, s54
	s_nop 0
	global_load_lds_dwordx4 v132, s[46:47]
	s_waitcnt vmcnt(8)
	s_waitcnt lgkmcnt(0)
	s_barrier
	s_setprio 1
	s_waitcnt lgkmcnt(0)
	v_mfma_f32_16x16x32_bf16 v[62:65], v[144:147], v[176:179], v[62:65]
	v_mfma_f32_16x16x32_bf16 v[58:61], v[152:155], v[176:179], v[58:61]
	v_mfma_f32_16x16x32_bf16 v[46:49], v[144:147], v[184:187], v[46:49]
	v_mfma_f32_16x16x32_bf16 v[42:45], v[152:155], v[184:187], v[42:45]
	v_mfma_f32_16x16x32_bf16 v[30:33], v[144:147], v[196:199], v[30:33]
	v_mfma_f32_16x16x32_bf16 v[26:29], v[152:155], v[196:199], v[26:29]
	v_mfma_f32_16x16x32_bf16 v[14:17], v[144:147], v[204:207], v[14:17]
	v_mfma_f32_16x16x32_bf16 v[10:13], v[152:155], v[204:207], v[10:13]
	v_mfma_f32_16x16x32_bf16 v[62:65], v[148:151], v[180:183], v[62:65]
	v_mfma_f32_16x16x32_bf16 v[58:61], v[156:159], v[180:183], v[58:61]
	v_mfma_f32_16x16x32_bf16 v[46:49], v[148:151], v[192:195], v[46:49]
	v_mfma_f32_16x16x32_bf16 v[42:45], v[156:159], v[192:195], v[42:45]
	v_mfma_f32_16x16x32_bf16 v[30:33], v[148:151], v[200:203], v[30:33]
	v_mfma_f32_16x16x32_bf16 v[26:29], v[156:159], v[200:203], v[26:29]
	v_mfma_f32_16x16x32_bf16 v[14:17], v[148:151], v[208:211], v[14:17]
	v_mfma_f32_16x16x32_bf16 v[10:13], v[156:159], v[208:211], v[10:13]
	s_setprio 0
	s_setprio 1
	v_mfma_f32_16x16x32_bf16 v[54:57], v[160:163], v[176:179], v[54:57]
	v_mfma_f32_16x16x32_bf16 v[50:53], v[168:171], v[176:179], v[50:53]
	v_mfma_f32_16x16x32_bf16 v[38:41], v[160:163], v[184:187], v[38:41]
	v_mfma_f32_16x16x32_bf16 v[34:37], v[168:171], v[184:187], v[34:37]
	v_mfma_f32_16x16x32_bf16 v[22:25], v[160:163], v[196:199], v[22:25]
	v_mfma_f32_16x16x32_bf16 v[18:21], v[168:171], v[196:199], v[18:21]
	v_mfma_f32_16x16x32_bf16 v[6:9], v[160:163], v[204:207], v[6:9]
	v_mfma_f32_16x16x32_bf16 v[2:5], v[168:171], v[204:207], v[2:5]
	v_mfma_f32_16x16x32_bf16 v[54:57], v[164:167], v[180:183], v[54:57]
	v_mfma_f32_16x16x32_bf16 v[50:53], v[172:175], v[180:183], v[50:53]
	v_mfma_f32_16x16x32_bf16 v[38:41], v[164:167], v[192:195], v[38:41]
	v_mfma_f32_16x16x32_bf16 v[34:37], v[172:175], v[192:195], v[34:37]
	v_mfma_f32_16x16x32_bf16 v[22:25], v[164:167], v[200:203], v[22:25]
	v_mfma_f32_16x16x32_bf16 v[18:21], v[172:175], v[200:203], v[18:21]
	v_mfma_f32_16x16x32_bf16 v[6:9], v[164:167], v[208:211], v[6:9]
	v_mfma_f32_16x16x32_bf16 v[2:5], v[172:175], v[208:211], v[2:5]
	s_setprio 0
	s_barrier
	s_cmp_ge_i32 s58, s55
	s_mov_b64 s[46:47], s[48:49]
	s_mov_b32 s50, s58
	s_cbranch_scc0 .LBB0_131

; #define PG8_STAGE(bufoff, gbase, voff) do { _Pragma("unroll") for (int _i = 0; _i < 2; ++_i) \
;         __builtin_amdgcn_global_load_lds((const unsigned*)((const char*)(gbase) + (voff)[_i]), (LAS unsigned*)(lds + (bufoff) + ldsw + _i * 8192), 16, 0, 0); } while (0)
; #define PG8_LDA(dst, b, h) do { _Pragma("unroll") for (int m = 0; m < 4; ++m) _Pragma("unroll") for (int k = 0; k < 2; ++k) dst[m][k] = *(const LAS bf16x8*)(lds + PG8_SA(b, h) + aoff + m * 2048 + k * 1024); } while (0)
; #define PG8_LDB(dst, b, h) do { _Pragma("unroll") for (int n = 0; n < 2; ++n) _Pragma("unroll") for (int k = 0; k < 2; ++k) dst[n][k] = *(const LAS bf16x8*)(lds + PG8_SB(b, h) + boff + n * 2048 + k * 1024); } while (0)
; #define PG8_MMA(ai, bj, At, Bt) do { __builtin_amdgcn_s_setprio(1); _Pragma("unroll") for (int m = 0; m < 4; ++m) _Pragma("unroll") for (int n = 0; n < 2; ++n) _Pragma("unroll") for (int k = 0; k < 2; ++k) \
;         acc[ai][bj][m][n] = __builtin_amdgcn_mfma_f32_16x16x32_bf16(Bt[n][k], At[m][k], acc[ai][bj][m][n], 0, 0, 0); __builtin_amdgcn_s_setprio(0); } while (0)
; #define PG8_WAIT_V(n) asm volatile("s_waitcnt vmcnt(" #n ")" ::: "memory")
; #define PG8_WAIT_L(n) asm volatile("s_waitcnt lgkmcnt(" #n ")" ::: "memory")
; #define PG8_BAR __builtin_amdgcn_s_barrier()
; template <class Epi, class Sched>
; __device__ __forceinline__ void gemm_phase(LAS unsigned char* lds, const Gemm g, const Sched& S, const Epi& E) {
;     ...
;         for (int t = 0; t < nt; t += 2) {
;             const bool last = (t == nt - 2);
;             const char* a1 = cA + (size_t)(t + 1) * kstep;
;             const char* a2 = last ? nA : cA + (size_t)(t + 2) * kstep; const char* b2 = last ? nB : cB + (size_t)(t + 2) * kstep;
;             const char* a3 = a2 + kstep; const char* b3 = b2 + kstep;
;             if (last && has_next) S.a_ready(nxt);
;             PG8_LDB(B0, 0, 0); PG8_LDB(B1, 0, 1); PG8_SCHED; PG8_LDA(At, 0, 0); PG8_STAGE(PG8_SA(1, 1), a1 + hstep, voffA);
;             PG8_WAIT_V(8); PG8_WAIT_L(0); PG8_BAR; PG8_MMA(0, 0, At, B0); PG8_MMA(0, 1, At, B1); PG8_BAR; PG8_SCHED;
;             PG8_LDA(At, 0, 1); PG8_STAGE(PG8_SB(0, 0), b2, voffB); PG8_STAGE(PG8_SB(0, 1), b2 + hstep, voffB); PG8_STAGE(PG8_SA(0, 0), a2, voffA);
;             PG8_WAIT_V(8); PG8_WAIT_L(0); PG8_BAR; PG8_MMA(1, 0, At, B0); PG8_MMA(1, 1, At, B1); PG8_BAR; PG8_SCHED;
.LBB0_418:
	s_add_i32 s58, s52, 2
	s_add_u32 s50, s48, 0x100
	s_addc_u32 s51, s49, 0
	s_add_u32 s1, s9, s48
	s_addc_u32 s53, s36, s49
	s_cmp_eq_u32 s56, s52
	s_cselect_b32 s52, 0, s50
	s_cselect_b32 s59, 0, s51
	s_cselect_b32 s60, s46, s1
	s_cselect_b32 s61, s47, s53
	s_add_u32 s52, s2, s52
	s_addc_u32 s53, s3, s59
	s_add_i32 s1, 0, 0x10000
	s_add_i32 s59, 0, 0x14000
	v_add_u32_e32 v154, s1, v160
	v_add_u32_e32 v158, s59, v160
	ds_read_b128 v[130:133], v154
	ds_read_b128 v[134:137], v154 offset:1024
	ds_read_b128 v[138:141], v154 offset:2048
	ds_read_b128 v[154:157], v154 offset:3072
	ds_read_b128 v[162:165], v158
	ds_read_b128 v[166:169], v158 offset:1024
	ds_read_b128 v[170:173], v158 offset:2048
	ds_read_b128 v[174:177], v158 offset:3072
	s_add_u32 s48, s48, s2
	s_addc_u32 s49, s49, s3
	s_add_u32 s48, s48, s26
	s_addc_u32 s49, s49, s27
	s_add_u32 s48, s48, 0x80
	s_addc_u32 s49, s49, 0
	s_add_i32 m0, s5, 0xc000
	ds_read_b128 v[178:181], v161
	ds_read_b128 v[182:185], v161 offset:1024
	ds_read_b128 v[192:195], v161 offset:2048
	ds_read_b128 v[196:199], v161 offset:3072
	ds_read_b128 v[200:203], v161 offset:4096
	ds_read_b128 v[204:207], v161 offset:5120
	ds_read_b128 v[208:211], v161 offset:6144
	ds_read_b128 v[212:215], v161 offset:7168
	global_load_lds_dwordx4 v146, s[48:49]
	s_add_i32 m0, s5, 0xe000
	s_nop 0
	global_load_lds_dwordx4 v144, s[48:49]
	s_waitcnt vmcnt(8)
	s_waitcnt lgkmcnt(0)
	s_barrier
	s_setprio 1
	s_waitcnt lgkmcnt(0)
	v_mfma_f32_16x16x32_bf16 v[122:125], v[130:133], v[178:181], v[122:125]
	v_mfma_f32_16x16x32_bf16 v[126:129], v[138:141], v[178:181], v[126:129]
	v_mfma_f32_16x16x32_bf16 v[110:113], v[130:133], v[192:195], v[110:113]
	v_mfma_f32_16x16x32_bf16 v[106:109], v[138:141], v[192:195], v[106:109]
	v_mfma_f32_16x16x32_bf16 v[94:97], v[130:133], v[200:203], v[94:97]
	v_mfma_f32_16x16x32_bf16 v[90:93], v[138:141], v[200:203], v[90:93]
	v_mfma_f32_16x16x32_bf16 v[78:81], v[130:133], v[208:211], v[78:81]
	v_mfma_f32_16x16x32_bf16 v[74:77], v[138:141], v[208:211], v[74:77]
	v_mfma_f32_16x16x32_bf16 v[122:125], v[134:137], v[182:185], v[122:125]
	v_mfma_f32_16x16x32_bf16 v[126:129], v[154:157], v[182:185], v[126:129]
	v_mfma_f32_16x16x32_bf16 v[110:113], v[134:137], v[196:199], v[110:113]
	v_mfma_f32_16x16x32_bf16 v[106:109], v[154:157], v[196:199], v[106:109]
	v_mfma_f32_16x16x32_bf16 v[94:97], v[134:137], v[204:207], v[94:97]
	v_mfma_f32_16x16x32_bf16 v[90:93], v[154:157], v[204:207], v[90:93]
	v_mfma_f32_16x16x32_bf16 v[78:81], v[134:137], v[212:215], v[78:81]
	v_mfma_f32_16x16x32_bf16 v[74:77], v[154:157], v[212:215], v[74:77]
	s_setprio 0
	s_setprio 1
	v_mfma_f32_16x16x32_bf16 v[118:121], v[162:165], v[178:181], v[118:121]
	v_mfma_f32_16x16x32_bf16 v[114:117], v[170:173], v[178:181], v[114:117]
	v_mfma_f32_16x16x32_bf16 v[102:105], v[162:165], v[192:195], v[102:105]
	v_mfma_f32_16x16x32_bf16 v[98:101], v[170:173], v[192:195], v[98:101]
	v_mfma_f32_16x16x32_bf16 v[86:89], v[162:165], v[200:203], v[86:89]
	v_mfma_f32_16x16x32_bf16 v[82:85], v[170:173], v[200:203], v[82:85]
	v_mfma_f32_16x16x32_bf16 v[70:73], v[162:165], v[208:211], v[70:73]
	v_mfma_f32_16x16x32_bf16 v[66:69], v[170:173], v[208:211], v[66:69]
	v_mfma_f32_16x16x32_bf16 v[118:121], v[166:169], v[182:185], v[118:121]
	v_mfma_f32_16x16x32_bf16 v[114:117], v[174:177], v[182:185], v[114:117]
	v_mfma_f32_16x16x32_bf16 v[102:105], v[166:169], v[196:199], v[102:105]
	v_mfma_f32_16x16x32_bf16 v[98:101], v[174:177], v[196:199], v[98:101]
	v_mfma_f32_16x16x32_bf16 v[86:89], v[166:169], v[204:207], v[86:89]
	v_mfma_f32_16x16x32_bf16 v[82:85], v[174:177], v[204:207], v[82:85]
	v_mfma_f32_16x16x32_bf16 v[70:73], v[166:169], v[212:215], v[70:73]
	v_mfma_f32_16x16x32_bf16 v[66:69], v[174:177], v[212:215], v[66:69]
	s_setprio 0
	s_barrier
	s_add_i32 s1, s1, s4
	s_mov_b32 m0, s1
	ds_read_b128 v[178:181], v161 offset:16384
	ds_read_b128 v[182:185], v161 offset:17408
	ds_read_b128 v[192:195], v161 offset:18432
	ds_read_b128 v[196:199], v161 offset:19456
	ds_read_b128 v[200:203], v161 offset:20480
	ds_read_b128 v[204:207], v161 offset:21504
	ds_read_b128 v[208:211], v161 offset:22528
	ds_read_b128 v[212:215], v161 offset:23552
	global_load_lds_dwordx4 v0, s[60:61]
	s_add_i32 m0, s1, 0x2000
	s_add_u32 s48, s60, s26
	s_addc_u32 s49, s61, s27
	s_add_i32 s1, s59, s4
	global_load_lds_dwordx4 v142, s[60:61]
	s_mov_b32 m0, s1
	s_nop 0
	global_load_lds_dwordx4 v0, s[48:49]
	s_add_i32 m0, s1, 0x2000
	s_nop 0
	global_load_lds_dwordx4 v142, s[48:49]
	s_mov_b32 m0, s5
	s_nop 0
	global_load_lds_dwordx4 v146, s[52:53]
	s_mov_b32 m0, s18
	s_nop 0
	global_load_lds_dwordx4 v144, s[52:53]
	s_waitcnt vmcnt(8)
	s_waitcnt lgkmcnt(0)
	s_barrier
; #define PG8_STAGE(bufoff, gbase, voff) do { _Pragma("unroll") for (int _i = 0; _i < 2; ++_i) \
;         __builtin_amdgcn_global_load_lds((const unsigned*)((const char*)(gbase) + (voff)[_i]), (LAS unsigned*)(lds + (bufoff) + ldsw + _i * 8192), 16, 0, 0); } while (0)
; #define PG8_LDA(dst, b, h) do { _Pragma("unroll") for (int m = 0; m < 4; ++m) _Pragma("unroll") for (int k = 0; k < 2; ++k) dst[m][k] = *(const LAS bf16x8*)(lds + PG8_SA(b, h) + aoff + m * 2048 + k * 1024); } while (0)
; #define PG8_LDB(dst, b, h) do { _Pragma("unroll") for (int n = 0; n < 2; ++n) _Pragma("unroll") for (int k = 0; k < 2; ++k) dst[n][k] = *(const LAS bf16x8*)(lds + PG8_SB(b, h) + boff + n * 2048 + k * 1024); } while (0)
; #define PG8_MMA(ai, bj, At, Bt) do { __builtin_amdgcn_s_setprio(1); _Pragma("unroll") for (int m = 0; m < 4; ++m) _Pragma("unroll") for (int n = 0; n < 2; ++n) _Pragma("unroll") for (int k = 0; k < 2; ++k) \
;         acc[ai][bj][m][n] = __builtin_amdgcn_mfma_f32_16x16x32_bf16(Bt[n][k], At[m][k], acc[ai][bj][m][n], 0, 0, 0); __builtin_amdgcn_s_setprio(0); } while (0)
; #define PG8_WAIT_V(n) asm volatile("s_waitcnt vmcnt(" #n ")" ::: "memory")
; #define PG8_WAIT_L(n) asm volatile("s_waitcnt lgkmcnt(" #n ")" ::: "memory")
; #define PG8_BAR __builtin_amdgcn_s_barrier()
; #define PG8_SCHED __builtin_amdgcn_sched_barrier(0)
; template <class Epi, class Sched>
; __device__ __forceinline__ void gemm_phase(LAS unsigned char* lds, const Gemm g, const Sched& S, const Epi& E) {
;     ...
;             PG8_WAIT_V(8); PG8_WAIT_L(0); PG8_BAR; PG8_MMA(1, 0, At, B0); PG8_MMA(1, 1, At, B1); PG8_BAR; PG8_SCHED;
;             PG8_LDB(B0, 1, 0); PG8_LDB(B1, 1, 1); PG8_SCHED; PG8_LDA(At, 1, 0); PG8_STAGE(PG8_SA(0, 1), a2 + hstep, voffA);
;             PG8_WAIT_V(8); PG8_WAIT_L(0); PG8_BAR; PG8_MMA(0, 0, At, B0); PG8_MMA(0, 1, At, B1); PG8_BAR; PG8_SCHED;
	s_setprio 1
	s_waitcnt lgkmcnt(0)
	v_mfma_f32_16x16x32_bf16 v[62:65], v[130:133], v[178:181], v[62:65]
	v_mfma_f32_16x16x32_bf16 v[58:61], v[138:141], v[178:181], v[58:61]
	v_mfma_f32_16x16x32_bf16 v[46:49], v[130:133], v[192:195], v[46:49]
	v_mfma_f32_16x16x32_bf16 v[42:45], v[138:141], v[192:195], v[42:45]
	v_mfma_f32_16x16x32_bf16 v[30:33], v[130:133], v[200:203], v[30:33]
	v_mfma_f32_16x16x32_bf16 v[26:29], v[138:141], v[200:203], v[26:29]
	v_mfma_f32_16x16x32_bf16 v[14:17], v[130:133], v[208:211], v[14:17]
	v_mfma_f32_16x16x32_bf16 v[10:13], v[138:141], v[208:211], v[10:13]
	v_mfma_f32_16x16x32_bf16 v[62:65], v[134:137], v[182:185], v[62:65]
	v_mfma_f32_16x16x32_bf16 v[58:61], v[154:157], v[182:185], v[58:61]
	v_mfma_f32_16x16x32_bf16 v[46:49], v[134:137], v[196:199], v[46:49]
	v_mfma_f32_16x16x32_bf16 v[42:45], v[154:157], v[196:199], v[42:45]
	v_mfma_f32_16x16x32_bf16 v[30:33], v[134:137], v[204:207], v[30:33]
	v_mfma_f32_16x16x32_bf16 v[26:29], v[154:157], v[204:207], v[26:29]
	v_mfma_f32_16x16x32_bf16 v[14:17], v[134:137], v[212:215], v[14:17]
	v_mfma_f32_16x16x32_bf16 v[10:13], v[154:157], v[212:215], v[10:13]
	s_setprio 0
	s_setprio 1
	v_mfma_f32_16x16x32_bf16 v[54:57], v[162:165], v[178:181], v[54:57]
	v_mfma_f32_16x16x32_bf16 v[50:53], v[170:173], v[178:181], v[50:53]
	v_mfma_f32_16x16x32_bf16 v[38:41], v[162:165], v[192:195], v[38:41]
	v_mfma_f32_16x16x32_bf16 v[34:37], v[170:173], v[192:195], v[34:37]
	v_mfma_f32_16x16x32_bf16 v[22:25], v[162:165], v[200:203], v[22:25]
	v_mfma_f32_16x16x32_bf16 v[18:21], v[170:173], v[200:203], v[18:21]
	v_mfma_f32_16x16x32_bf16 v[6:9], v[162:165], v[208:211], v[6:9]
	v_mfma_f32_16x16x32_bf16 v[2:5], v[170:173], v[208:211], v[2:5]
	v_mfma_f32_16x16x32_bf16 v[54:57], v[166:169], v[182:185], v[54:57]
	v_mfma_f32_16x16x32_bf16 v[50:53], v[174:177], v[182:185], v[50:53]
	v_mfma_f32_16x16x32_bf16 v[38:41], v[166:169], v[196:199], v[38:41]
	v_mfma_f32_16x16x32_bf16 v[34:37], v[174:177], v[196:199], v[34:37]
	v_mfma_f32_16x16x32_bf16 v[22:25], v[166:169], v[204:207], v[22:25]
	v_mfma_f32_16x16x32_bf16 v[18:21], v[174:177], v[204:207], v[18:21]
	v_mfma_f32_16x16x32_bf16 v[6:9], v[166:169], v[212:215], v[6:9]
	v_mfma_f32_16x16x32_bf16 v[2:5], v[174:177], v[212:215], v[2:5]
	s_setprio 0
	s_barrier
	s_add_i32 s1, 0, 0x18000
	s_add_i32 s59, 0, 0x1c000
	v_add_u32_e32 v154, s1, v160
	v_add_u32_e32 v174, s59, v160
	ds_read_b128 v[130:133], v154
	ds_read_b128 v[134:137], v154 offset:1024
	ds_read_b128 v[138:141], v154 offset:2048
	ds_read_b128 v[154:157], v154 offset:3072
	ds_read_b128 v[162:165], v174
	ds_read_b128 v[166:169], v174 offset:1024
	ds_read_b128 v[170:173], v174 offset:2048
	ds_read_b128 v[174:177], v174 offset:3072
	s_add_u32 s48, s52, s26
	s_addc_u32 s49, s53, s27
	s_mov_b32 m0, s19
	ds_read_b128 v[178:181], v161 offset:32768
	ds_read_b128 v[182:185], v161 offset:33792
	ds_read_b128 v[192:195], v161 offset:34816
	ds_read_b128 v[196:199], v161 offset:35840
	ds_read_b128 v[200:203], v161 offset:36864
	ds_read_b128 v[204:207], v161 offset:37888
	ds_read_b128 v[208:211], v161 offset:38912
	ds_read_b128 v[212:215], v161 offset:39936
	global_load_lds_dwordx4 v146, s[48:49]
	s_mov_b32 m0, s20
	s_nop 0
	global_load_lds_dwordx4 v144, s[48:49]
	s_waitcnt vmcnt(8)
	s_waitcnt lgkmcnt(0)
	s_barrier
	s_setprio 1
	s_waitcnt lgkmcnt(0)
	v_mfma_f32_16x16x32_bf16 v[122:125], v[130:133], v[178:181], v[122:125]
	v_mfma_f32_16x16x32_bf16 v[126:129], v[138:141], v[178:181], v[126:129]
	v_mfma_f32_16x16x32_bf16 v[110:113], v[130:133], v[192:195], v[110:113]
	v_mfma_f32_16x16x32_bf16 v[106:109], v[138:141], v[192:195], v[106:109]
	v_mfma_f32_16x16x32_bf16 v[94:97], v[130:133], v[200:203], v[94:97]
	v_mfma_f32_16x16x32_bf16 v[90:93], v[138:141], v[200:203], v[90:93]
	v_mfma_f32_16x16x32_bf16 v[78:81], v[130:133], v[208:211], v[78:81]
	v_mfma_f32_16x16x32_bf16 v[74:77], v[138:141], v[208:211], v[74:77]
	v_mfma_f32_16x16x32_bf16 v[122:125], v[134:137], v[182:185], v[122:125]
	v_mfma_f32_16x16x32_bf16 v[126:129], v[154:157], v[182:185], v[126:129]
	v_mfma_f32_16x16x32_bf16 v[110:113], v[134:137], v[196:199], v[110:113]
	v_mfma_f32_16x16x32_bf16 v[106:109], v[154:157], v[196:199], v[106:109]
	v_mfma_f32_16x16x32_bf16 v[94:97], v[134:137], v[204:207], v[94:97]
	v_mfma_f32_16x16x32_bf16 v[90:93], v[154:157], v[204:207], v[90:93]
	v_mfma_f32_16x16x32_bf16 v[78:81], v[134:137], v[212:215], v[78:81]
	v_mfma_f32_16x16x32_bf16 v[74:77], v[154:157], v[212:215], v[74:77]
	s_setprio 0
	s_setprio 1
	v_mfma_f32_16x16x32_bf16 v[118:121], v[162:165], v[178:181], v[118:121]
	v_mfma_f32_16x16x32_bf16 v[114:117], v[170:173], v[178:181], v[114:117]
	v_mfma_f32_16x16x32_bf16 v[102:105], v[162:165], v[192:195], v[102:105]
	v_mfma_f32_16x16x32_bf16 v[98:101], v[170:173], v[192:195], v[98:101]
	v_mfma_f32_16x16x32_bf16 v[86:89], v[162:165], v[200:203], v[86:89]
	v_mfma_f32_16x16x32_bf16 v[82:85], v[170:173], v[200:203], v[82:85]
	v_mfma_f32_16x16x32_bf16 v[70:73], v[162:165], v[208:211], v[70:73]
	v_mfma_f32_16x16x32_bf16 v[66:69], v[170:173], v[208:211], v[66:69]
	v_mfma_f32_16x16x32_bf16 v[118:121], v[166:169], v[182:185], v[118:121]
	v_mfma_f32_16x16x32_bf16 v[114:117], v[174:177], v[182:185], v[114:117]
	v_mfma_f32_16x16x32_bf16 v[102:105], v[166:169], v[196:199], v[102:105]
	v_mfma_f32_16x16x32_bf16 v[98:101], v[174:177], v[196:199], v[98:101]
	v_mfma_f32_16x16x32_bf16 v[86:89], v[166:169], v[204:207], v[86:89]
	v_mfma_f32_16x16x32_bf16 v[82:85], v[174:177], v[204:207], v[82:85]
	v_mfma_f32_16x16x32_bf16 v[70:73], v[166:169], v[212:215], v[70:73]
	v_mfma_f32_16x16x32_bf16 v[66:69], v[174:177], v[212:215], v[66:69]
	s_setprio 0
	s_barrier
; #define PG8_STAGE(bufoff, gbase, voff) do { _Pragma("unroll") for (int _i = 0; _i < 2; ++_i) \
;         __builtin_amdgcn_global_load_lds((const unsigned*)((const char*)(gbase) + (voff)[_i]), (LAS unsigned*)(lds + (bufoff) + ldsw + _i * 8192), 16, 0, 0); } while (0)
; #define PG8_LDA(dst, b, h) do { _Pragma("unroll") for (int m = 0; m < 4; ++m) _Pragma("unroll") for (int k = 0; k < 2; ++k) dst[m][k] = *(const LAS bf16x8*)(lds + PG8_SA(b, h) + aoff + m * 2048 + k * 1024); } while (0)
; #define PG8_MMA(ai, bj, At, Bt) do { __builtin_amdgcn_s_setprio(1); _Pragma("unroll") for (int m = 0; m < 4; ++m) _Pragma("unroll") for (int n = 0; n < 2; ++n) _Pragma("unroll") for (int k = 0; k < 2; ++k) \
;         acc[ai][bj][m][n] = __builtin_amdgcn_mfma_f32_16x16x32_bf16(Bt[n][k], At[m][k], acc[ai][bj][m][n], 0, 0, 0); __builtin_amdgcn_s_setprio(0); } while (0)
; #define PG8_WAIT_V(n) asm volatile("s_waitcnt vmcnt(" #n ")" ::: "memory")
; #define PG8_WAIT_L(n) asm volatile("s_waitcnt lgkmcnt(" #n ")" ::: "memory")
; #define PG8_BAR __builtin_amdgcn_s_barrier()
; #define PG8_SCHED __builtin_amdgcn_sched_barrier(0)
; template <class Epi, class Sched>
; __device__ __forceinline__ void gemm_phase(LAS unsigned char* lds, const Gemm g, const Sched& S, const Epi& E) {
;     ...
;             PG8_LDA(At, 1, 1); PG8_STAGE(PG8_SB(1, 0), b3, voffB); PG8_STAGE(PG8_SB(1, 1), b3 + hstep, voffB); PG8_STAGE(PG8_SA(1, 0), a3, voffA);
;             PG8_WAIT_V(8); PG8_WAIT_L(0); PG8_BAR; PG8_MMA(1, 0, At, B0); PG8_MMA(1, 1, At, B1); PG8_BAR; PG8_SCHED;
;         }
	s_add_i32 s1, s1, s4
	s_add_u32 s48, s60, 0x80
	s_addc_u32 s49, s61, 0
	s_mov_b32 m0, s1
	ds_read_b128 v[178:181], v161 offset:49152
	ds_read_b128 v[182:185], v161 offset:50176
	ds_read_b128 v[192:195], v161 offset:51200
	ds_read_b128 v[196:199], v161 offset:52224
	ds_read_b128 v[200:203], v161 offset:53248
	ds_read_b128 v[204:207], v161 offset:54272
	ds_read_b128 v[208:211], v161 offset:55296
	ds_read_b128 v[212:215], v161 offset:56320
	global_load_lds_dwordx4 v0, s[48:49]
	s_add_i32 m0, s1, 0x2000
	s_add_i32 s1, s59, s4
	global_load_lds_dwordx4 v142, s[48:49]
	s_add_u32 s48, s48, s26
	s_addc_u32 s49, s49, s27
	s_mov_b32 m0, s1
	s_nop 0
	global_load_lds_dwordx4 v0, s[48:49]
	s_add_i32 m0, s1, 0x2000
	s_nop 0
	global_load_lds_dwordx4 v142, s[48:49]
	s_add_u32 s48, s52, 0x80
	s_addc_u32 s49, s53, 0
	s_mov_b32 m0, s54
	s_nop 0
	global_load_lds_dwordx4 v146, s[48:49]
	s_mov_b32 m0, s55
	s_nop 0
	global_load_lds_dwordx4 v144, s[48:49]
	s_waitcnt vmcnt(8)
	s_waitcnt lgkmcnt(0)
	s_barrier
	s_setprio 1
	s_waitcnt lgkmcnt(0)
	v_mfma_f32_16x16x32_bf16 v[62:65], v[130:133], v[178:181], v[62:65]
	v_mfma_f32_16x16x32_bf16 v[58:61], v[138:141], v[178:181], v[58:61]
	v_mfma_f32_16x16x32_bf16 v[46:49], v[130:133], v[192:195], v[46:49]
	v_mfma_f32_16x16x32_bf16 v[42:45], v[138:141], v[192:195], v[42:45]
	v_mfma_f32_16x16x32_bf16 v[30:33], v[130:133], v[200:203], v[30:33]
	v_mfma_f32_16x16x32_bf16 v[26:29], v[138:141], v[200:203], v[26:29]
	v_mfma_f32_16x16x32_bf16 v[14:17], v[130:133], v[208:211], v[14:17]
	v_mfma_f32_16x16x32_bf16 v[10:13], v[138:141], v[208:211], v[10:13]
	v_mfma_f32_16x16x32_bf16 v[62:65], v[134:137], v[182:185], v[62:65]
	v_mfma_f32_16x16x32_bf16 v[58:61], v[154:157], v[182:185], v[58:61]
	v_mfma_f32_16x16x32_bf16 v[46:49], v[134:137], v[196:199], v[46:49]
	v_mfma_f32_16x16x32_bf16 v[42:45], v[154:157], v[196:199], v[42:45]
	v_mfma_f32_16x16x32_bf16 v[30:33], v[134:137], v[204:207], v[30:33]
	v_mfma_f32_16x16x32_bf16 v[26:29], v[154:157], v[204:207], v[26:29]
	v_mfma_f32_16x16x32_bf16 v[14:17], v[134:137], v[212:215], v[14:17]
	v_mfma_f32_16x16x32_bf16 v[10:13], v[154:157], v[212:215], v[10:13]
	s_setprio 0
	s_setprio 1
	v_mfma_f32_16x16x32_bf16 v[54:57], v[162:165], v[178:181], v[54:57]
	v_mfma_f32_16x16x32_bf16 v[50:53], v[170:173], v[178:181], v[50:53]
	v_mfma_f32_16x16x32_bf16 v[38:41], v[162:165], v[192:195], v[38:41]
	v_mfma_f32_16x16x32_bf16 v[34:37], v[170:173], v[192:195], v[34:37]
	v_mfma_f32_16x16x32_bf16 v[22:25], v[162:165], v[200:203], v[22:25]
	v_mfma_f32_16x16x32_bf16 v[18:21], v[170:173], v[200:203], v[18:21]
	v_mfma_f32_16x16x32_bf16 v[6:9], v[162:165], v[208:211], v[6:9]
	v_mfma_f32_16x16x32_bf16 v[2:5], v[170:173], v[208:211], v[2:5]
	v_mfma_f32_16x16x32_bf16 v[54:57], v[166:169], v[182:185], v[54:57]
	v_mfma_f32_16x16x32_bf16 v[50:53], v[174:177], v[182:185], v[50:53]
	v_mfma_f32_16x16x32_bf16 v[38:41], v[166:169], v[196:199], v[38:41]
	v_mfma_f32_16x16x32_bf16 v[34:37], v[174:177], v[196:199], v[34:37]
	v_mfma_f32_16x16x32_bf16 v[22:25], v[166:169], v[204:207], v[22:25]
	v_mfma_f32_16x16x32_bf16 v[18:21], v[174:177], v[204:207], v[18:21]
	v_mfma_f32_16x16x32_bf16 v[6:9], v[166:169], v[212:215], v[6:9]
	v_mfma_f32_16x16x32_bf16 v[2:5], v[174:177], v[212:215], v[2:5]
	s_setprio 0
	s_barrier
	s_cmp_ge_i32 s58, s21
	s_mov_b64 s[48:49], s[50:51]
	s_mov_b32 s52, s58
	s_cbranch_scc0 .LBB0_418

; #define PG8_STAGE(bufoff, gbase, voff) do { _Pragma("unroll") for (int _i = 0; _i < 2; ++_i) \
;         __builtin_amdgcn_global_load_lds((const unsigned*)((const char*)(gbase) + (voff)[_i]), (LAS unsigned*)(lds + (bufoff) + ldsw + _i * 8192), 16, 0, 0); } while (0)
; #define PG8_LDA(dst, b, h) do { _Pragma("unroll") for (int m = 0; m < 4; ++m) _Pragma("unroll") for (int k = 0; k < 2; ++k) dst[m][k] = *(const LAS bf16x8*)(lds + PG8_SA(b, h) + aoff + m * 2048 + k * 1024); } while (0)
; #define PG8_LDB(dst, b, h) do { _Pragma("unroll") for (int n = 0; n < 2; ++n) _Pragma("unroll") for (int k = 0; k < 2; ++k) dst[n][k] = *(const LAS bf16x8*)(lds + PG8_SB(b, h) + boff + n * 2048 + k * 1024); } while (0)
; #define PG8_MMA(ai, bj, At, Bt) do { __builtin_amdgcn_s_setprio(1); _Pragma("unroll") for (int m = 0; m < 4; ++m) _Pragma("unroll") for (int n = 0; n < 2; ++n) _Pragma("unroll") for (int k = 0; k < 2; ++k) \
;         acc[ai][bj][m][n] = __builtin_amdgcn_mfma_f32_16x16x32_bf16(Bt[n][k], At[m][k], acc[ai][bj][m][n], 0, 0, 0); __builtin_amdgcn_s_setprio(0); } while (0)
; #define PG8_WAIT_V(n) asm volatile("s_waitcnt vmcnt(" #n ")" ::: "memory")
; #define PG8_WAIT_L(n) asm volatile("s_waitcnt lgkmcnt(" #n ")" ::: "memory")
; #define PG8_BAR __builtin_amdgcn_s_barrier()
; template <class Epi, class Sched>
; __device__ __forceinline__ void gemm_phase(LAS unsigned char* lds, const Gemm g, const Sched& S, const Epi& E) {
;     ...
;         for (int t = 0; t < nt; t += 2) {
;             const bool last = (t == nt - 2);
;             const char* a1 = cA + (size_t)(t + 1) * kstep;
;             const char* a2 = last ? nA : cA + (size_t)(t + 2) * kstep; const char* b2 = last ? nB : cB + (size_t)(t + 2) * kstep;
;             const char* a3 = a2 + kstep; const char* b3 = b2 + kstep;
;             if (last && has_next) S.a_ready(nxt);
;             PG8_LDB(B0, 0, 0); PG8_LDB(B1, 0, 1); PG8_SCHED; PG8_LDA(At, 0, 0); PG8_STAGE(PG8_SA(1, 1), a1 + hstep, voffA);
;             PG8_WAIT_V(8); PG8_WAIT_L(0); PG8_BAR; PG8_MMA(0, 0, At, B0); PG8_MMA(0, 1, At, B1); PG8_BAR; PG8_SCHED;
;             PG8_LDA(At, 0, 1); PG8_STAGE(PG8_SB(0, 0), b2, voffB); PG8_STAGE(PG8_SB(0, 1), b2 + hstep, voffB); PG8_STAGE(PG8_SA(0, 0), a2, voffA);
;             PG8_WAIT_V(8); PG8_WAIT_L(0); PG8_BAR; PG8_MMA(1, 0, At, B0); PG8_MMA(1, 1, At, B1); PG8_BAR; PG8_SCHED;
.LBB0_435:
	s_add_i32 s62, s52, 2
	s_add_u32 s50, s48, 0x100
	s_addc_u32 s51, s49, 0
	s_add_u32 s1, s9, s48
	s_addc_u32 s53, s36, s49
	s_cmp_eq_u32 s60, s52
	s_cselect_b32 s52, s100, s50
	s_cselect_b32 s63, 0, s51
	s_cselect_b32 s64, s46, s1
	s_cselect_b32 s65, s47, s53
	s_add_u32 s52, s2, s52
	s_addc_u32 s53, s3, s63
	s_add_i32 s1, 0, 0x10000
	s_add_i32 s63, 0, 0x14000
	v_add_u32_e32 v156, s1, v142
	v_add_u32_e32 v172, s63, v142
	ds_read_b128 v[144:147], v156
	ds_read_b128 v[148:151], v156 offset:1024
	ds_read_b128 v[152:155], v156 offset:2048
	ds_read_b128 v[156:159], v156 offset:3072
	ds_read_b128 v[160:163], v172
	ds_read_b128 v[164:167], v172 offset:1024
	ds_read_b128 v[168:171], v172 offset:2048
	ds_read_b128 v[172:175], v172 offset:3072
	s_add_u32 s48, s48, s2
	s_addc_u32 s49, s49, s3
	s_add_u32 s48, s48, s26
	s_addc_u32 s49, s49, s27
	s_add_u32 s48, s48, 0x80
	s_addc_u32 s49, s49, 0
	s_add_i32 m0, s5, 0xc000
	ds_read_b128 v[176:179], v143
	ds_read_b128 v[180:183], v143 offset:1024
	ds_read_b128 v[184:187], v143 offset:2048
	ds_read_b128 v[192:195], v143 offset:3072
	ds_read_b128 v[196:199], v143 offset:4096
	ds_read_b128 v[200:203], v143 offset:5120
	ds_read_b128 v[204:207], v143 offset:6144
	ds_read_b128 v[208:211], v143 offset:7168
	global_load_lds_dwordx4 v134, s[48:49]
	s_add_i32 m0, s5, 0xe000
	s_nop 0
	global_load_lds_dwordx4 v132, s[48:49]
	s_waitcnt vmcnt(8)
	s_waitcnt lgkmcnt(0)
	s_barrier
	s_setprio 1
	s_waitcnt lgkmcnt(0)
	v_mfma_f32_16x16x32_bf16 v[122:125], v[144:147], v[176:179], v[122:125]
	v_mfma_f32_16x16x32_bf16 v[126:129], v[152:155], v[176:179], v[126:129]
	v_mfma_f32_16x16x32_bf16 v[110:113], v[144:147], v[184:187], v[110:113]
	v_mfma_f32_16x16x32_bf16 v[106:109], v[152:155], v[184:187], v[106:109]
	v_mfma_f32_16x16x32_bf16 v[94:97], v[144:147], v[196:199], v[94:97]
	v_mfma_f32_16x16x32_bf16 v[90:93], v[152:155], v[196:199], v[90:93]
	v_mfma_f32_16x16x32_bf16 v[78:81], v[144:147], v[204:207], v[78:81]
	v_mfma_f32_16x16x32_bf16 v[74:77], v[152:155], v[204:207], v[74:77]
	v_mfma_f32_16x16x32_bf16 v[122:125], v[148:151], v[180:183], v[122:125]
	v_mfma_f32_16x16x32_bf16 v[126:129], v[156:159], v[180:183], v[126:129]
	v_mfma_f32_16x16x32_bf16 v[110:113], v[148:151], v[192:195], v[110:113]
	v_mfma_f32_16x16x32_bf16 v[106:109], v[156:159], v[192:195], v[106:109]
	v_mfma_f32_16x16x32_bf16 v[94:97], v[148:151], v[200:203], v[94:97]
	v_mfma_f32_16x16x32_bf16 v[90:93], v[156:159], v[200:203], v[90:93]
	v_mfma_f32_16x16x32_bf16 v[78:81], v[148:151], v[208:211], v[78:81]
	v_mfma_f32_16x16x32_bf16 v[74:77], v[156:159], v[208:211], v[74:77]
	s_setprio 0
	s_setprio 1
	v_mfma_f32_16x16x32_bf16 v[118:121], v[160:163], v[176:179], v[118:121]
	v_mfma_f32_16x16x32_bf16 v[114:117], v[168:171], v[176:179], v[114:117]
	v_mfma_f32_16x16x32_bf16 v[102:105], v[160:163], v[184:187], v[102:105]
	v_mfma_f32_16x16x32_bf16 v[98:101], v[168:171], v[184:187], v[98:101]
	v_mfma_f32_16x16x32_bf16 v[86:89], v[160:163], v[196:199], v[86:89]
	v_mfma_f32_16x16x32_bf16 v[82:85], v[168:171], v[196:199], v[82:85]
	v_mfma_f32_16x16x32_bf16 v[70:73], v[160:163], v[204:207], v[70:73]
	v_mfma_f32_16x16x32_bf16 v[66:69], v[168:171], v[204:207], v[66:69]
	v_mfma_f32_16x16x32_bf16 v[118:121], v[164:167], v[180:183], v[118:121]
	v_mfma_f32_16x16x32_bf16 v[114:117], v[172:175], v[180:183], v[114:117]
	v_mfma_f32_16x16x32_bf16 v[102:105], v[164:167], v[192:195], v[102:105]
	v_mfma_f32_16x16x32_bf16 v[98:101], v[172:175], v[192:195], v[98:101]
	v_mfma_f32_16x16x32_bf16 v[86:89], v[164:167], v[200:203], v[86:89]
	v_mfma_f32_16x16x32_bf16 v[82:85], v[172:175], v[200:203], v[82:85]
	v_mfma_f32_16x16x32_bf16 v[70:73], v[164:167], v[208:211], v[70:73]
	v_mfma_f32_16x16x32_bf16 v[66:69], v[172:175], v[208:211], v[66:69]
	s_setprio 0
	s_barrier
	s_add_i32 s1, s1, s4
	s_mov_b32 m0, s1
	ds_read_b128 v[176:179], v143 offset:16384
	ds_read_b128 v[180:183], v143 offset:17408
	ds_read_b128 v[184:187], v143 offset:18432
	ds_read_b128 v[192:195], v143 offset:19456
	ds_read_b128 v[196:199], v143 offset:20480
	ds_read_b128 v[200:203], v143 offset:21504
	ds_read_b128 v[204:207], v143 offset:22528
	ds_read_b128 v[208:211], v143 offset:23552
	global_load_lds_dwordx4 v0, s[64:65]
	s_add_i32 m0, s1, 0x2000
	s_add_u32 s48, s64, s26
	s_addc_u32 s49, s65, s27
	s_add_i32 s1, s63, s4
	global_load_lds_dwordx4 v130, s[64:65]
	s_mov_b32 m0, s1
	s_nop 0
	global_load_lds_dwordx4 v0, s[48:49]
	s_add_i32 m0, s1, 0x2000
	s_nop 0
	global_load_lds_dwordx4 v130, s[48:49]
	s_mov_b32 m0, s5
	s_nop 0
	global_load_lds_dwordx4 v134, s[52:53]
	s_mov_b32 m0, s54
	s_nop 0
	global_load_lds_dwordx4 v132, s[52:53]
	s_waitcnt vmcnt(8)
	s_waitcnt lgkmcnt(0)
	s_barrier
; #define PG8_STAGE(bufoff, gbase, voff) do { _Pragma("unroll") for (int _i = 0; _i < 2; ++_i) \
;         __builtin_amdgcn_global_load_lds((const unsigned*)((const char*)(gbase) + (voff)[_i]), (LAS unsigned*)(lds + (bufoff) + ldsw + _i * 8192), 16, 0, 0); } while (0)
; #define PG8_LDA(dst, b, h) do { _Pragma("unroll") for (int m = 0; m < 4; ++m) _Pragma("unroll") for (int k = 0; k < 2; ++k) dst[m][k] = *(const LAS bf16x8*)(lds + PG8_SA(b, h) + aoff + m * 2048 + k * 1024); } while (0)
; #define PG8_LDB(dst, b, h) do { _Pragma("unroll") for (int n = 0; n < 2; ++n) _Pragma("unroll") for (int k = 0; k < 2; ++k) dst[n][k] = *(const LAS bf16x8*)(lds + PG8_SB(b, h) + boff + n * 2048 + k * 1024); } while (0)
; #define PG8_MMA(ai, bj, At, Bt) do { __builtin_amdgcn_s_setprio(1); _Pragma("unroll") for (int m = 0; m < 4; ++m) _Pragma("unroll") for (int n = 0; n < 2; ++n) _Pragma("unroll") for (int k = 0; k < 2; ++k) \
;         acc[ai][bj][m][n] = __builtin_amdgcn_mfma_f32_16x16x32_bf16(Bt[n][k], At[m][k], acc[ai][bj][m][n], 0, 0, 0); __builtin_amdgcn_s_setprio(0); } while (0)
; #define PG8_WAIT_V(n) asm volatile("s_waitcnt vmcnt(" #n ")" ::: "memory")
; #define PG8_WAIT_L(n) asm volatile("s_waitcnt lgkmcnt(" #n ")" ::: "memory")
; #define PG8_BAR __builtin_amdgcn_s_barrier()
; #define PG8_SCHED __builtin_amdgcn_sched_barrier(0)
; template <class Epi, class Sched>
; __device__ __forceinline__ void gemm_phase(LAS unsigned char* lds, const Gemm g, const Sched& S, const Epi& E) {
;     ...
;             PG8_WAIT_V(8); PG8_WAIT_L(0); PG8_BAR; PG8_MMA(1, 0, At, B0); PG8_MMA(1, 1, At, B1); PG8_BAR; PG8_SCHED;
;             PG8_LDB(B0, 1, 0); PG8_LDB(B1, 1, 1); PG8_SCHED; PG8_LDA(At, 1, 0); PG8_STAGE(PG8_SA(0, 1), a2 + hstep, voffA);
;             PG8_WAIT_V(8); PG8_WAIT_L(0); PG8_BAR; PG8_MMA(0, 0, At, B0); PG8_MMA(0, 1, At, B1); PG8_BAR; PG8_SCHED;
	s_setprio 1
	s_waitcnt lgkmcnt(0)
	v_mfma_f32_16x16x32_bf16 v[62:65], v[144:147], v[176:179], v[62:65]
	v_mfma_f32_16x16x32_bf16 v[58:61], v[152:155], v[176:179], v[58:61]
	v_mfma_f32_16x16x32_bf16 v[46:49], v[144:147], v[184:187], v[46:49]
	v_mfma_f32_16x16x32_bf16 v[42:45], v[152:155], v[184:187], v[42:45]
	v_mfma_f32_16x16x32_bf16 v[30:33], v[144:147], v[196:199], v[30:33]
	v_mfma_f32_16x16x32_bf16 v[26:29], v[152:155], v[196:199], v[26:29]
	v_mfma_f32_16x16x32_bf16 v[14:17], v[144:147], v[204:207], v[14:17]
	v_mfma_f32_16x16x32_bf16 v[10:13], v[152:155], v[204:207], v[10:13]
	v_mfma_f32_16x16x32_bf16 v[62:65], v[148:151], v[180:183], v[62:65]
	v_mfma_f32_16x16x32_bf16 v[58:61], v[156:159], v[180:183], v[58:61]
	v_mfma_f32_16x16x32_bf16 v[46:49], v[148:151], v[192:195], v[46:49]
	v_mfma_f32_16x16x32_bf16 v[42:45], v[156:159], v[192:195], v[42:45]
	v_mfma_f32_16x16x32_bf16 v[30:33], v[148:151], v[200:203], v[30:33]
	v_mfma_f32_16x16x32_bf16 v[26:29], v[156:159], v[200:203], v[26:29]
	v_mfma_f32_16x16x32_bf16 v[14:17], v[148:151], v[208:211], v[14:17]
	v_mfma_f32_16x16x32_bf16 v[10:13], v[156:159], v[208:211], v[10:13]
	s_setprio 0
	s_setprio 1
	v_mfma_f32_16x16x32_bf16 v[54:57], v[160:163], v[176:179], v[54:57]
	v_mfma_f32_16x16x32_bf16 v[50:53], v[168:171], v[176:179], v[50:53]
	v_mfma_f32_16x16x32_bf16 v[38:41], v[160:163], v[184:187], v[38:41]
	v_mfma_f32_16x16x32_bf16 v[34:37], v[168:171], v[184:187], v[34:37]
	v_mfma_f32_16x16x32_bf16 v[22:25], v[160:163], v[196:199], v[22:25]
	v_mfma_f32_16x16x32_bf16 v[18:21], v[168:171], v[196:199], v[18:21]
	v_mfma_f32_16x16x32_bf16 v[6:9], v[160:163], v[204:207], v[6:9]
	v_mfma_f32_16x16x32_bf16 v[2:5], v[168:171], v[204:207], v[2:5]
	v_mfma_f32_16x16x32_bf16 v[54:57], v[164:167], v[180:183], v[54:57]
	v_mfma_f32_16x16x32_bf16 v[50:53], v[172:175], v[180:183], v[50:53]
	v_mfma_f32_16x16x32_bf16 v[38:41], v[164:167], v[192:195], v[38:41]
	v_mfma_f32_16x16x32_bf16 v[34:37], v[172:175], v[192:195], v[34:37]
	v_mfma_f32_16x16x32_bf16 v[22:25], v[164:167], v[200:203], v[22:25]
	v_mfma_f32_16x16x32_bf16 v[18:21], v[172:175], v[200:203], v[18:21]
	v_mfma_f32_16x16x32_bf16 v[6:9], v[164:167], v[208:211], v[6:9]
	v_mfma_f32_16x16x32_bf16 v[2:5], v[172:175], v[208:211], v[2:5]
	s_setprio 0
	s_barrier
	s_add_i32 s1, 0, 0x18000
	s_add_i32 s63, 0, 0x1c000
	v_add_u32_e32 v156, s1, v142
	v_add_u32_e32 v172, s63, v142
	ds_read_b128 v[144:147], v156
	ds_read_b128 v[148:151], v156 offset:1024
	ds_read_b128 v[152:155], v156 offset:2048
	ds_read_b128 v[156:159], v156 offset:3072
	ds_read_b128 v[160:163], v172
	ds_read_b128 v[164:167], v172 offset:1024
	ds_read_b128 v[168:171], v172 offset:2048
	ds_read_b128 v[172:175], v172 offset:3072
	s_add_u32 s48, s52, s26
	s_addc_u32 s49, s53, s27
	s_mov_b32 m0, s55
	ds_read_b128 v[176:179], v143 offset:32768
	ds_read_b128 v[180:183], v143 offset:33792
	ds_read_b128 v[184:187], v143 offset:34816
	ds_read_b128 v[192:195], v143 offset:35840
	ds_read_b128 v[196:199], v143 offset:36864
	ds_read_b128 v[200:203], v143 offset:37888
	ds_read_b128 v[204:207], v143 offset:38912
	ds_read_b128 v[208:211], v143 offset:39936
	global_load_lds_dwordx4 v134, s[48:49]
	s_mov_b32 m0, s56
	s_nop 0
	global_load_lds_dwordx4 v132, s[48:49]
	s_waitcnt vmcnt(8)
	s_waitcnt lgkmcnt(0)
	s_barrier
	s_setprio 1
	s_waitcnt lgkmcnt(0)
	v_mfma_f32_16x16x32_bf16 v[122:125], v[144:147], v[176:179], v[122:125]
	v_mfma_f32_16x16x32_bf16 v[126:129], v[152:155], v[176:179], v[126:129]
	v_mfma_f32_16x16x32_bf16 v[110:113], v[144:147], v[184:187], v[110:113]
	v_mfma_f32_16x16x32_bf16 v[106:109], v[152:155], v[184:187], v[106:109]
	v_mfma_f32_16x16x32_bf16 v[94:97], v[144:147], v[196:199], v[94:97]
	v_mfma_f32_16x16x32_bf16 v[90:93], v[152:155], v[196:199], v[90:93]
	v_mfma_f32_16x16x32_bf16 v[78:81], v[144:147], v[204:207], v[78:81]
	v_mfma_f32_16x16x32_bf16 v[74:77], v[152:155], v[204:207], v[74:77]
	v_mfma_f32_16x16x32_bf16 v[122:125], v[148:151], v[180:183], v[122:125]
	v_mfma_f32_16x16x32_bf16 v[126:129], v[156:159], v[180:183], v[126:129]
	v_mfma_f32_16x16x32_bf16 v[110:113], v[148:151], v[192:195], v[110:113]
	v_mfma_f32_16x16x32_bf16 v[106:109], v[156:159], v[192:195], v[106:109]
	v_mfma_f32_16x16x32_bf16 v[94:97], v[148:151], v[200:203], v[94:97]
	v_mfma_f32_16x16x32_bf16 v[90:93], v[156:159], v[200:203], v[90:93]
	v_mfma_f32_16x16x32_bf16 v[78:81], v[148:151], v[208:211], v[78:81]
	v_mfma_f32_16x16x32_bf16 v[74:77], v[156:159], v[208:211], v[74:77]
	s_setprio 0
	s_setprio 1
	v_mfma_f32_16x16x32_bf16 v[118:121], v[160:163], v[176:179], v[118:121]
	v_mfma_f32_16x16x32_bf16 v[114:117], v[168:171], v[176:179], v[114:117]
	v_mfma_f32_16x16x32_bf16 v[102:105], v[160:163], v[184:187], v[102:105]
	v_mfma_f32_16x16x32_bf16 v[98:101], v[168:171], v[184:187], v[98:101]
	v_mfma_f32_16x16x32_bf16 v[86:89], v[160:163], v[196:199], v[86:89]
	v_mfma_f32_16x16x32_bf16 v[82:85], v[168:171], v[196:199], v[82:85]
	v_mfma_f32_16x16x32_bf16 v[70:73], v[160:163], v[204:207], v[70:73]
	v_mfma_f32_16x16x32_bf16 v[66:69], v[168:171], v[204:207], v[66:69]
	v_mfma_f32_16x16x32_bf16 v[118:121], v[164:167], v[180:183], v[118:121]
	v_mfma_f32_16x16x32_bf16 v[114:117], v[172:175], v[180:183], v[114:117]
	v_mfma_f32_16x16x32_bf16 v[102:105], v[164:167], v[192:195], v[102:105]
	v_mfma_f32_16x16x32_bf16 v[98:101], v[172:175], v[192:195], v[98:101]
	v_mfma_f32_16x16x32_bf16 v[86:89], v[164:167], v[200:203], v[86:89]
	v_mfma_f32_16x16x32_bf16 v[82:85], v[172:175], v[200:203], v[82:85]
	v_mfma_f32_16x16x32_bf16 v[70:73], v[164:167], v[208:211], v[70:73]
	v_mfma_f32_16x16x32_bf16 v[66:69], v[172:175], v[208:211], v[66:69]
	s_setprio 0
	s_barrier
; #define PG8_STAGE(bufoff, gbase, voff) do { _Pragma("unroll") for (int _i = 0; _i < 2; ++_i) \
;         __builtin_amdgcn_global_load_lds((const unsigned*)((const char*)(gbase) + (voff)[_i]), (LAS unsigned*)(lds + (bufoff) + ldsw + _i * 8192), 16, 0, 0); } while (0)
; #define PG8_LDA(dst, b, h) do { _Pragma("unroll") for (int m = 0; m < 4; ++m) _Pragma("unroll") for (int k = 0; k < 2; ++k) dst[m][k] = *(const LAS bf16x8*)(lds + PG8_SA(b, h) + aoff + m * 2048 + k * 1024); } while (0)
; #define PG8_MMA(ai, bj, At, Bt) do { __builtin_amdgcn_s_setprio(1); _Pragma("unroll") for (int m = 0; m < 4; ++m) _Pragma("unroll") for (int n = 0; n < 2; ++n) _Pragma("unroll") for (int k = 0; k < 2; ++k) \
;         acc[ai][bj][m][n] = __builtin_amdgcn_mfma_f32_16x16x32_bf16(Bt[n][k], At[m][k], acc[ai][bj][m][n], 0, 0, 0); __builtin_amdgcn_s_setprio(0); } while (0)
; #define PG8_WAIT_V(n) asm volatile("s_waitcnt vmcnt(" #n ")" ::: "memory")
; #define PG8_WAIT_L(n) asm volatile("s_waitcnt lgkmcnt(" #n ")" ::: "memory")
; #define PG8_BAR __builtin_amdgcn_s_barrier()
; #define PG8_SCHED __builtin_amdgcn_sched_barrier(0)
; template <class Epi, class Sched>
; __device__ __forceinline__ void gemm_phase(LAS unsigned char* lds, const Gemm g, const Sched& S, const Epi& E) {
;     ...
;             PG8_LDA(At, 1, 1); PG8_STAGE(PG8_SB(1, 0), b3, voffB); PG8_STAGE(PG8_SB(1, 1), b3 + hstep, voffB); PG8_STAGE(PG8_SA(1, 0), a3, voffA);
;             PG8_WAIT_V(8); PG8_WAIT_L(0); PG8_BAR; PG8_MMA(1, 0, At, B0); PG8_MMA(1, 1, At, B1); PG8_BAR; PG8_SCHED;
;         }
	s_add_i32 s1, s1, s4
	s_add_u32 s48, s64, 0x80
	s_addc_u32 s49, s65, 0
	s_mov_b32 m0, s1
	ds_read_b128 v[176:179], v143 offset:49152
	ds_read_b128 v[180:183], v143 offset:50176
	ds_read_b128 v[184:187], v143 offset:51200
	ds_read_b128 v[192:195], v143 offset:52224
	ds_read_b128 v[196:199], v143 offset:53248
	ds_read_b128 v[200:203], v143 offset:54272
	ds_read_b128 v[204:207], v143 offset:55296
	ds_read_b128 v[208:211], v143 offset:56320
	global_load_lds_dwordx4 v0, s[48:49]
	s_add_i32 m0, s1, 0x2000
	s_add_i32 s1, s63, s4
	global_load_lds_dwordx4 v130, s[48:49]
	s_add_u32 s48, s48, s26
	s_addc_u32 s49, s49, s27
	s_mov_b32 m0, s1
	s_nop 0
	global_load_lds_dwordx4 v0, s[48:49]
	s_add_i32 m0, s1, 0x2000
	s_nop 0
	global_load_lds_dwordx4 v130, s[48:49]
	s_add_u32 s48, s52, 0x80
	s_addc_u32 s49, s53, 0
	s_mov_b32 m0, s57
	s_nop 0
	global_load_lds_dwordx4 v134, s[48:49]
	s_mov_b32 m0, s58
	s_nop 0
	global_load_lds_dwordx4 v132, s[48:49]
	s_waitcnt vmcnt(8)
	s_waitcnt lgkmcnt(0)
	s_barrier
	s_setprio 1
	s_waitcnt lgkmcnt(0)
	v_mfma_f32_16x16x32_bf16 v[62:65], v[144:147], v[176:179], v[62:65]
	v_mfma_f32_16x16x32_bf16 v[58:61], v[152:155], v[176:179], v[58:61]
	v_mfma_f32_16x16x32_bf16 v[46:49], v[144:147], v[184:187], v[46:49]
	v_mfma_f32_16x16x32_bf16 v[42:45], v[152:155], v[184:187], v[42:45]
	v_mfma_f32_16x16x32_bf16 v[30:33], v[144:147], v[196:199], v[30:33]
	v_mfma_f32_16x16x32_bf16 v[26:29], v[152:155], v[196:199], v[26:29]
	v_mfma_f32_16x16x32_bf16 v[14:17], v[144:147], v[204:207], v[14:17]
	v_mfma_f32_16x16x32_bf16 v[10:13], v[152:155], v[204:207], v[10:13]
	v_mfma_f32_16x16x32_bf16 v[62:65], v[148:151], v[180:183], v[62:65]
	v_mfma_f32_16x16x32_bf16 v[58:61], v[156:159], v[180:183], v[58:61]
	v_mfma_f32_16x16x32_bf16 v[46:49], v[148:151], v[192:195], v[46:49]
	v_mfma_f32_16x16x32_bf16 v[42:45], v[156:159], v[192:195], v[42:45]
	v_mfma_f32_16x16x32_bf16 v[30:33], v[148:151], v[200:203], v[30:33]
	v_mfma_f32_16x16x32_bf16 v[26:29], v[156:159], v[200:203], v[26:29]
	v_mfma_f32_16x16x32_bf16 v[14:17], v[148:151], v[208:211], v[14:17]
	v_mfma_f32_16x16x32_bf16 v[10:13], v[156:159], v[208:211], v[10:13]
	s_setprio 0
	s_setprio 1
	v_mfma_f32_16x16x32_bf16 v[54:57], v[160:163], v[176:179], v[54:57]
	v_mfma_f32_16x16x32_bf16 v[50:53], v[168:171], v[176:179], v[50:53]
	v_mfma_f32_16x16x32_bf16 v[38:41], v[160:163], v[184:187], v[38:41]
	v_mfma_f32_16x16x32_bf16 v[34:37], v[168:171], v[184:187], v[34:37]
	v_mfma_f32_16x16x32_bf16 v[22:25], v[160:163], v[196:199], v[22:25]
	v_mfma_f32_16x16x32_bf16 v[18:21], v[168:171], v[196:199], v[18:21]
	v_mfma_f32_16x16x32_bf16 v[6:9], v[160:163], v[204:207], v[6:9]
	v_mfma_f32_16x16x32_bf16 v[2:5], v[168:171], v[204:207], v[2:5]
	v_mfma_f32_16x16x32_bf16 v[54:57], v[164:167], v[180:183], v[54:57]
	v_mfma_f32_16x16x32_bf16 v[50:53], v[172:175], v[180:183], v[50:53]
	v_mfma_f32_16x16x32_bf16 v[38:41], v[164:167], v[192:195], v[38:41]
	v_mfma_f32_16x16x32_bf16 v[34:37], v[172:175], v[192:195], v[34:37]
	v_mfma_f32_16x16x32_bf16 v[22:25], v[164:167], v[200:203], v[22:25]
	v_mfma_f32_16x16x32_bf16 v[18:21], v[172:175], v[200:203], v[18:21]
	v_mfma_f32_16x16x32_bf16 v[6:9], v[164:167], v[208:211], v[6:9]
	v_mfma_f32_16x16x32_bf16 v[2:5], v[172:175], v[208:211], v[2:5]
	s_setprio 0
	s_barrier
	s_cmp_ge_i32 s62, s59
	s_mov_b64 s[48:49], s[50:51]
	s_mov_b32 s52, s62
	s_cbranch_scc0 .LBB0_435

; #define PG8_STAGE(bufoff, gbase, voff) do { _Pragma("unroll") for (int _i = 0; _i < 2; ++_i) \
;         __builtin_amdgcn_global_load_lds((const unsigned*)((const char*)(gbase) + (voff)[_i]), (LAS unsigned*)(lds + (bufoff) + ldsw + _i * 8192), 16, 0, 0); } while (0)
; #define PG8_LDA(dst, b, h) do { _Pragma("unroll") for (int m = 0; m < 4; ++m) _Pragma("unroll") for (int k = 0; k < 2; ++k) dst[m][k] = *(const LAS bf16x8*)(lds + PG8_SA(b, h) + aoff + m * 2048 + k * 1024); } while (0)
; #define PG8_LDB(dst, b, h) do { _Pragma("unroll") for (int n = 0; n < 2; ++n) _Pragma("unroll") for (int k = 0; k < 2; ++k) dst[n][k] = *(const LAS bf16x8*)(lds + PG8_SB(b, h) + boff + n * 2048 + k * 1024); } while (0)
; #define PG8_MMA(ai, bj, At, Bt) do { __builtin_amdgcn_s_setprio(1); _Pragma("unroll") for (int m = 0; m < 4; ++m) _Pragma("unroll") for (int n = 0; n < 2; ++n) _Pragma("unroll") for (int k = 0; k < 2; ++k) \
;         acc[ai][bj][m][n] = __builtin_amdgcn_mfma_f32_16x16x32_bf16(Bt[n][k], At[m][k], acc[ai][bj][m][n], 0, 0, 0); __builtin_amdgcn_s_setprio(0); } while (0)
; #define PG8_WAIT_V(n) asm volatile("s_waitcnt vmcnt(" #n ")" ::: "memory")
; #define PG8_WAIT_L(n) asm volatile("s_waitcnt lgkmcnt(" #n ")" ::: "memory")
; #define PG8_BAR __builtin_amdgcn_s_barrier()
; template <class Epi, class Sched>
; __device__ __forceinline__ void gemm_phase(LAS unsigned char* lds, const Gemm g, const Sched& S, const Epi& E) {
;     ...
;         for (int t = 0; t < nt; t += 2) {
;             const bool last = (t == nt - 2);
;             const char* a1 = cA + (size_t)(t + 1) * kstep;
;             const char* a2 = last ? nA : cA + (size_t)(t + 2) * kstep; const char* b2 = last ? nB : cB + (size_t)(t + 2) * kstep;
;             const char* a3 = a2 + kstep; const char* b3 = b2 + kstep;
;             if (last && has_next) S.a_ready(nxt);
;             PG8_LDB(B0, 0, 0); PG8_LDB(B1, 0, 1); PG8_SCHED; PG8_LDA(At, 0, 0); PG8_STAGE(PG8_SA(1, 1), a1 + hstep, voffA);
;             PG8_WAIT_V(8); PG8_WAIT_L(0); PG8_BAR; PG8_MMA(0, 0, At, B0); PG8_MMA(0, 1, At, B1); PG8_BAR; PG8_SCHED;
;             PG8_LDA(At, 0, 1); PG8_STAGE(PG8_SB(0, 0), b2, voffB); PG8_STAGE(PG8_SB(0, 1), b2 + hstep, voffB); PG8_STAGE(PG8_SA(0, 0), a2, voffA);
;             PG8_WAIT_V(8); PG8_WAIT_L(0); PG8_BAR; PG8_MMA(1, 0, At, B0); PG8_MMA(1, 1, At, B1); PG8_BAR; PG8_SCHED;
.LBB0_450:
	s_add_i32 s60, s50, 2
	s_add_u32 s48, s46, 0x100
	s_addc_u32 s49, s47, 0
	s_add_u32 s1, s9, s46
	s_addc_u32 s51, s36, s47
	s_cmp_eq_u32 s58, s50
	s_cselect_b32 s50, 0xff000000, s48
	s_cselect_b32 s61, -1, s49
	s_cselect_b32 s62, s44, s1
	s_cselect_b32 s63, s45, s51
	s_add_u32 s50, s2, s50
	s_addc_u32 s51, s3, s61
	s_add_i32 s1, 0, 0x10000
	s_add_i32 s61, 0, 0x14000
	v_add_u32_e32 v154, s1, v160
	v_add_u32_e32 v158, s61, v160
	ds_read_b128 v[130:133], v154
	ds_read_b128 v[134:137], v154 offset:1024
	ds_read_b128 v[138:141], v154 offset:2048
	ds_read_b128 v[154:157], v154 offset:3072
	ds_read_b128 v[162:165], v158
	ds_read_b128 v[166:169], v158 offset:1024
	ds_read_b128 v[170:173], v158 offset:2048
	ds_read_b128 v[174:177], v158 offset:3072
	s_add_u32 s46, s46, s2
	s_addc_u32 s47, s47, s3
	s_add_u32 s46, s46, s18
	s_addc_u32 s47, s47, s19
	s_add_u32 s46, s46, 0x80
	s_addc_u32 s47, s47, 0
	s_add_i32 m0, s5, 0xc000
	ds_read_b128 v[178:181], v161
	ds_read_b128 v[182:185], v161 offset:1024
	ds_read_b128 v[192:195], v161 offset:2048
	ds_read_b128 v[196:199], v161 offset:3072
	ds_read_b128 v[200:203], v161 offset:4096
	ds_read_b128 v[204:207], v161 offset:5120
	ds_read_b128 v[208:211], v161 offset:6144
	ds_read_b128 v[212:215], v161 offset:7168
	global_load_lds_dwordx4 v146, s[46:47]
	s_add_i32 m0, s5, 0xe000
	s_nop 0
	global_load_lds_dwordx4 v144, s[46:47]
	s_waitcnt vmcnt(8)
	s_waitcnt lgkmcnt(0)
	s_barrier
	s_setprio 1
	s_waitcnt lgkmcnt(0)
	v_mfma_f32_16x16x32_bf16 v[122:125], v[130:133], v[178:181], v[122:125]
	v_mfma_f32_16x16x32_bf16 v[126:129], v[138:141], v[178:181], v[126:129]
	v_mfma_f32_16x16x32_bf16 v[110:113], v[130:133], v[192:195], v[110:113]
	v_mfma_f32_16x16x32_bf16 v[106:109], v[138:141], v[192:195], v[106:109]
	v_mfma_f32_16x16x32_bf16 v[94:97], v[130:133], v[200:203], v[94:97]
	v_mfma_f32_16x16x32_bf16 v[90:93], v[138:141], v[200:203], v[90:93]
	v_mfma_f32_16x16x32_bf16 v[78:81], v[130:133], v[208:211], v[78:81]
	v_mfma_f32_16x16x32_bf16 v[74:77], v[138:141], v[208:211], v[74:77]
	v_mfma_f32_16x16x32_bf16 v[122:125], v[134:137], v[182:185], v[122:125]
	v_mfma_f32_16x16x32_bf16 v[126:129], v[154:157], v[182:185], v[126:129]
	v_mfma_f32_16x16x32_bf16 v[110:113], v[134:137], v[196:199], v[110:113]
	v_mfma_f32_16x16x32_bf16 v[106:109], v[154:157], v[196:199], v[106:109]
	v_mfma_f32_16x16x32_bf16 v[94:97], v[134:137], v[204:207], v[94:97]
	v_mfma_f32_16x16x32_bf16 v[90:93], v[154:157], v[204:207], v[90:93]
	v_mfma_f32_16x16x32_bf16 v[78:81], v[134:137], v[212:215], v[78:81]
	v_mfma_f32_16x16x32_bf16 v[74:77], v[154:157], v[212:215], v[74:77]
	s_setprio 0
	s_setprio 1
	v_mfma_f32_16x16x32_bf16 v[118:121], v[162:165], v[178:181], v[118:121]
	v_mfma_f32_16x16x32_bf16 v[114:117], v[170:173], v[178:181], v[114:117]
	v_mfma_f32_16x16x32_bf16 v[102:105], v[162:165], v[192:195], v[102:105]
	v_mfma_f32_16x16x32_bf16 v[98:101], v[170:173], v[192:195], v[98:101]
	v_mfma_f32_16x16x32_bf16 v[86:89], v[162:165], v[200:203], v[86:89]
	v_mfma_f32_16x16x32_bf16 v[82:85], v[170:173], v[200:203], v[82:85]
	v_mfma_f32_16x16x32_bf16 v[70:73], v[162:165], v[208:211], v[70:73]
	v_mfma_f32_16x16x32_bf16 v[66:69], v[170:173], v[208:211], v[66:69]
	v_mfma_f32_16x16x32_bf16 v[118:121], v[166:169], v[182:185], v[118:121]
	v_mfma_f32_16x16x32_bf16 v[114:117], v[174:177], v[182:185], v[114:117]
	v_mfma_f32_16x16x32_bf16 v[102:105], v[166:169], v[196:199], v[102:105]
	v_mfma_f32_16x16x32_bf16 v[98:101], v[174:177], v[196:199], v[98:101]
	v_mfma_f32_16x16x32_bf16 v[86:89], v[166:169], v[204:207], v[86:89]
	v_mfma_f32_16x16x32_bf16 v[82:85], v[174:177], v[204:207], v[82:85]
	v_mfma_f32_16x16x32_bf16 v[70:73], v[166:169], v[212:215], v[70:73]
	v_mfma_f32_16x16x32_bf16 v[66:69], v[174:177], v[212:215], v[66:69]
	s_setprio 0
	s_barrier
	s_add_i32 s1, s1, s4
	s_mov_b32 m0, s1
	ds_read_b128 v[178:181], v161 offset:16384
	ds_read_b128 v[182:185], v161 offset:17408
	ds_read_b128 v[192:195], v161 offset:18432
	ds_read_b128 v[196:199], v161 offset:19456
	ds_read_b128 v[200:203], v161 offset:20480
	ds_read_b128 v[204:207], v161 offset:21504
	ds_read_b128 v[208:211], v161 offset:22528
	ds_read_b128 v[212:215], v161 offset:23552
	global_load_lds_dwordx4 v0, s[62:63]
	s_add_i32 m0, s1, 0x2000
	s_add_u32 s46, s62, s18
	s_addc_u32 s47, s63, s19
	s_add_i32 s1, s61, s4
	global_load_lds_dwordx4 v142, s[62:63]
	s_mov_b32 m0, s1
	s_nop 0
	global_load_lds_dwordx4 v0, s[46:47]
	s_add_i32 m0, s1, 0x2000
	s_nop 0
	global_load_lds_dwordx4 v142, s[46:47]
	s_mov_b32 m0, s5
	s_nop 0
	global_load_lds_dwordx4 v146, s[50:51]
	s_mov_b32 m0, s52
	s_nop 0
	global_load_lds_dwordx4 v144, s[50:51]
	s_waitcnt vmcnt(8)
	s_waitcnt lgkmcnt(0)
	s_barrier
; #define PG8_STAGE(bufoff, gbase, voff) do { _Pragma("unroll") for (int _i = 0; _i < 2; ++_i) \
;         __builtin_amdgcn_global_load_lds((const unsigned*)((const char*)(gbase) + (voff)[_i]), (LAS unsigned*)(lds + (bufoff) + ldsw + _i * 8192), 16, 0, 0); } while (0)
; #define PG8_LDA(dst, b, h) do { _Pragma("unroll") for (int m = 0; m < 4; ++m) _Pragma("unroll") for (int k = 0; k < 2; ++k) dst[m][k] = *(const LAS bf16x8*)(lds + PG8_SA(b, h) + aoff + m * 2048 + k * 1024); } while (0)
; #define PG8_LDB(dst, b, h) do { _Pragma("unroll") for (int n = 0; n < 2; ++n) _Pragma("unroll") for (int k = 0; k < 2; ++k) dst[n][k] = *(const LAS bf16x8*)(lds + PG8_SB(b, h) + boff + n * 2048 + k * 1024); } while (0)
; #define PG8_MMA(ai, bj, At, Bt) do { __builtin_amdgcn_s_setprio(1); _Pragma("unroll") for (int m = 0; m < 4; ++m) _Pragma("unroll") for (int n = 0; n < 2; ++n) _Pragma("unroll") for (int k = 0; k < 2; ++k) \
;         acc[ai][bj][m][n] = __builtin_amdgcn_mfma_f32_16x16x32_bf16(Bt[n][k], At[m][k], acc[ai][bj][m][n], 0, 0, 0); __builtin_amdgcn_s_setprio(0); } while (0)
; #define PG8_WAIT_V(n) asm volatile("s_waitcnt vmcnt(" #n ")" ::: "memory")
; #define PG8_WAIT_L(n) asm volatile("s_waitcnt lgkmcnt(" #n ")" ::: "memory")
; #define PG8_BAR __builtin_amdgcn_s_barrier()
; #define PG8_SCHED __builtin_amdgcn_sched_barrier(0)
; template <class Epi, class Sched>
; __device__ __forceinline__ void gemm_phase(LAS unsigned char* lds, const Gemm g, const Sched& S, const Epi& E) {
;     ...
;             PG8_WAIT_V(8); PG8_WAIT_L(0); PG8_BAR; PG8_MMA(1, 0, At, B0); PG8_MMA(1, 1, At, B1); PG8_BAR; PG8_SCHED;
;             PG8_LDB(B0, 1, 0); PG8_LDB(B1, 1, 1); PG8_SCHED; PG8_LDA(At, 1, 0); PG8_STAGE(PG8_SA(0, 1), a2 + hstep, voffA);
;             PG8_WAIT_V(8); PG8_WAIT_L(0); PG8_BAR; PG8_MMA(0, 0, At, B0); PG8_MMA(0, 1, At, B1); PG8_BAR; PG8_SCHED;
	s_setprio 1
	s_waitcnt lgkmcnt(0)
	v_mfma_f32_16x16x32_bf16 v[62:65], v[130:133], v[178:181], v[62:65]
	v_mfma_f32_16x16x32_bf16 v[58:61], v[138:141], v[178:181], v[58:61]
	v_mfma_f32_16x16x32_bf16 v[46:49], v[130:133], v[192:195], v[46:49]
	v_mfma_f32_16x16x32_bf16 v[42:45], v[138:141], v[192:195], v[42:45]
	v_mfma_f32_16x16x32_bf16 v[30:33], v[130:133], v[200:203], v[30:33]
	v_mfma_f32_16x16x32_bf16 v[26:29], v[138:141], v[200:203], v[26:29]
	v_mfma_f32_16x16x32_bf16 v[14:17], v[130:133], v[208:211], v[14:17]
	v_mfma_f32_16x16x32_bf16 v[10:13], v[138:141], v[208:211], v[10:13]
	v_mfma_f32_16x16x32_bf16 v[62:65], v[134:137], v[182:185], v[62:65]
	v_mfma_f32_16x16x32_bf16 v[58:61], v[154:157], v[182:185], v[58:61]
	v_mfma_f32_16x16x32_bf16 v[46:49], v[134:137], v[196:199], v[46:49]
	v_mfma_f32_16x16x32_bf16 v[42:45], v[154:157], v[196:199], v[42:45]
	v_mfma_f32_16x16x32_bf16 v[30:33], v[134:137], v[204:207], v[30:33]
	v_mfma_f32_16x16x32_bf16 v[26:29], v[154:157], v[204:207], v[26:29]
	v_mfma_f32_16x16x32_bf16 v[14:17], v[134:137], v[212:215], v[14:17]
	v_mfma_f32_16x16x32_bf16 v[10:13], v[154:157], v[212:215], v[10:13]
	s_setprio 0
	s_setprio 1
	v_mfma_f32_16x16x32_bf16 v[54:57], v[162:165], v[178:181], v[54:57]
	v_mfma_f32_16x16x32_bf16 v[50:53], v[170:173], v[178:181], v[50:53]
	v_mfma_f32_16x16x32_bf16 v[38:41], v[162:165], v[192:195], v[38:41]
	v_mfma_f32_16x16x32_bf16 v[34:37], v[170:173], v[192:195], v[34:37]
	v_mfma_f32_16x16x32_bf16 v[22:25], v[162:165], v[200:203], v[22:25]
	v_mfma_f32_16x16x32_bf16 v[18:21], v[170:173], v[200:203], v[18:21]
	v_mfma_f32_16x16x32_bf16 v[6:9], v[162:165], v[208:211], v[6:9]
	v_mfma_f32_16x16x32_bf16 v[2:5], v[170:173], v[208:211], v[2:5]
	v_mfma_f32_16x16x32_bf16 v[54:57], v[166:169], v[182:185], v[54:57]
	v_mfma_f32_16x16x32_bf16 v[50:53], v[174:177], v[182:185], v[50:53]
	v_mfma_f32_16x16x32_bf16 v[38:41], v[166:169], v[196:199], v[38:41]
	v_mfma_f32_16x16x32_bf16 v[34:37], v[174:177], v[196:199], v[34:37]
	v_mfma_f32_16x16x32_bf16 v[22:25], v[166:169], v[204:207], v[22:25]
	v_mfma_f32_16x16x32_bf16 v[18:21], v[174:177], v[204:207], v[18:21]
	v_mfma_f32_16x16x32_bf16 v[6:9], v[166:169], v[212:215], v[6:9]
	v_mfma_f32_16x16x32_bf16 v[2:5], v[174:177], v[212:215], v[2:5]
	s_setprio 0
	s_barrier
	s_add_i32 s1, 0, 0x18000
	s_add_i32 s61, 0, 0x1c000
	v_add_u32_e32 v154, s1, v160
	v_add_u32_e32 v174, s61, v160
	ds_read_b128 v[130:133], v154
	ds_read_b128 v[134:137], v154 offset:1024
	ds_read_b128 v[138:141], v154 offset:2048
	ds_read_b128 v[154:157], v154 offset:3072
	ds_read_b128 v[162:165], v174
	ds_read_b128 v[166:169], v174 offset:1024
	ds_read_b128 v[170:173], v174 offset:2048
	ds_read_b128 v[174:177], v174 offset:3072
	s_add_u32 s46, s50, s18
	s_addc_u32 s47, s51, s19
	s_mov_b32 m0, s53
	ds_read_b128 v[178:181], v161 offset:32768
	ds_read_b128 v[182:185], v161 offset:33792
	ds_read_b128 v[192:195], v161 offset:34816
	ds_read_b128 v[196:199], v161 offset:35840
	ds_read_b128 v[200:203], v161 offset:36864
	ds_read_b128 v[204:207], v161 offset:37888
	ds_read_b128 v[208:211], v161 offset:38912
	ds_read_b128 v[212:215], v161 offset:39936
	global_load_lds_dwordx4 v146, s[46:47]
	s_mov_b32 m0, s54
	s_nop 0
	global_load_lds_dwordx4 v144, s[46:47]
	s_waitcnt vmcnt(8)
	s_waitcnt lgkmcnt(0)
	s_barrier
	s_setprio 1
	s_waitcnt lgkmcnt(0)
	v_mfma_f32_16x16x32_bf16 v[122:125], v[130:133], v[178:181], v[122:125]
	v_mfma_f32_16x16x32_bf16 v[126:129], v[138:141], v[178:181], v[126:129]
	v_mfma_f32_16x16x32_bf16 v[110:113], v[130:133], v[192:195], v[110:113]
	v_mfma_f32_16x16x32_bf16 v[106:109], v[138:141], v[192:195], v[106:109]
	v_mfma_f32_16x16x32_bf16 v[94:97], v[130:133], v[200:203], v[94:97]
	v_mfma_f32_16x16x32_bf16 v[90:93], v[138:141], v[200:203], v[90:93]
	v_mfma_f32_16x16x32_bf16 v[78:81], v[130:133], v[208:211], v[78:81]
	v_mfma_f32_16x16x32_bf16 v[74:77], v[138:141], v[208:211], v[74:77]
	v_mfma_f32_16x16x32_bf16 v[122:125], v[134:137], v[182:185], v[122:125]
	v_mfma_f32_16x16x32_bf16 v[126:129], v[154:157], v[182:185], v[126:129]
	v_mfma_f32_16x16x32_bf16 v[110:113], v[134:137], v[196:199], v[110:113]
	v_mfma_f32_16x16x32_bf16 v[106:109], v[154:157], v[196:199], v[106:109]
	v_mfma_f32_16x16x32_bf16 v[94:97], v[134:137], v[204:207], v[94:97]
	v_mfma_f32_16x16x32_bf16 v[90:93], v[154:157], v[204:207], v[90:93]
	v_mfma_f32_16x16x32_bf16 v[78:81], v[134:137], v[212:215], v[78:81]
	v_mfma_f32_16x16x32_bf16 v[74:77], v[154:157], v[212:215], v[74:77]
	s_setprio 0
	s_setprio 1
	v_mfma_f32_16x16x32_bf16 v[118:121], v[162:165], v[178:181], v[118:121]
	v_mfma_f32_16x16x32_bf16 v[114:117], v[170:173], v[178:181], v[114:117]
	v_mfma_f32_16x16x32_bf16 v[102:105], v[162:165], v[192:195], v[102:105]
	v_mfma_f32_16x16x32_bf16 v[98:101], v[170:173], v[192:195], v[98:101]
	v_mfma_f32_16x16x32_bf16 v[86:89], v[162:165], v[200:203], v[86:89]
	v_mfma_f32_16x16x32_bf16 v[82:85], v[170:173], v[200:203], v[82:85]
	v_mfma_f32_16x16x32_bf16 v[70:73], v[162:165], v[208:211], v[70:73]
	v_mfma_f32_16x16x32_bf16 v[66:69], v[170:173], v[208:211], v[66:69]
	v_mfma_f32_16x16x32_bf16 v[118:121], v[166:169], v[182:185], v[118:121]
	v_mfma_f32_16x16x32_bf16 v[114:117], v[174:177], v[182:185], v[114:117]
	v_mfma_f32_16x16x32_bf16 v[102:105], v[166:169], v[196:199], v[102:105]
	v_mfma_f32_16x16x32_bf16 v[98:101], v[174:177], v[196:199], v[98:101]
	v_mfma_f32_16x16x32_bf16 v[86:89], v[166:169], v[204:207], v[86:89]
	v_mfma_f32_16x16x32_bf16 v[82:85], v[174:177], v[204:207], v[82:85]
	v_mfma_f32_16x16x32_bf16 v[70:73], v[166:169], v[212:215], v[70:73]
	v_mfma_f32_16x16x32_bf16 v[66:69], v[174:177], v[212:215], v[66:69]
	s_setprio 0
	s_barrier
; #define PG8_STAGE(bufoff, gbase, voff) do { _Pragma("unroll") for (int _i = 0; _i < 2; ++_i) \
;         __builtin_amdgcn_global_load_lds((const unsigned*)((const char*)(gbase) + (voff)[_i]), (LAS unsigned*)(lds + (bufoff) + ldsw + _i * 8192), 16, 0, 0); } while (0)
; #define PG8_LDA(dst, b, h) do { _Pragma("unroll") for (int m = 0; m < 4; ++m) _Pragma("unroll") for (int k = 0; k < 2; ++k) dst[m][k] = *(const LAS bf16x8*)(lds + PG8_SA(b, h) + aoff + m * 2048 + k * 1024); } while (0)
; #define PG8_MMA(ai, bj, At, Bt) do { __builtin_amdgcn_s_setprio(1); _Pragma("unroll") for (int m = 0; m < 4; ++m) _Pragma("unroll") for (int n = 0; n < 2; ++n) _Pragma("unroll") for (int k = 0; k < 2; ++k) \
;         acc[ai][bj][m][n] = __builtin_amdgcn_mfma_f32_16x16x32_bf16(Bt[n][k], At[m][k], acc[ai][bj][m][n], 0, 0, 0); __builtin_amdgcn_s_setprio(0); } while (0)
; #define PG8_WAIT_V(n) asm volatile("s_waitcnt vmcnt(" #n ")" ::: "memory")
; #define PG8_WAIT_L(n) asm volatile("s_waitcnt lgkmcnt(" #n ")" ::: "memory")
; #define PG8_BAR __builtin_amdgcn_s_barrier()
; #define PG8_SCHED __builtin_amdgcn_sched_barrier(0)
; template <class Epi, class Sched>
; __device__ __forceinline__ void gemm_phase(LAS unsigned char* lds, const Gemm g, const Sched& S, const Epi& E) {
;     ...
;             PG8_LDA(At, 1, 1); PG8_STAGE(PG8_SB(1, 0), b3, voffB); PG8_STAGE(PG8_SB(1, 1), b3 + hstep, voffB); PG8_STAGE(PG8_SA(1, 0), a3, voffA);
;             PG8_WAIT_V(8); PG8_WAIT_L(0); PG8_BAR; PG8_MMA(1, 0, At, B0); PG8_MMA(1, 1, At, B1); PG8_BAR; PG8_SCHED;
;         }
	s_add_i32 s1, s1, s4
	s_add_u32 s46, s62, 0x80
	s_addc_u32 s47, s63, 0
	s_mov_b32 m0, s1
	ds_read_b128 v[178:181], v161 offset:49152
	ds_read_b128 v[182:185], v161 offset:50176
	ds_read_b128 v[192:195], v161 offset:51200
	ds_read_b128 v[196:199], v161 offset:52224
	ds_read_b128 v[200:203], v161 offset:53248
	ds_read_b128 v[204:207], v161 offset:54272
	ds_read_b128 v[208:211], v161 offset:55296
	ds_read_b128 v[212:215], v161 offset:56320
	global_load_lds_dwordx4 v0, s[46:47]
	s_add_i32 m0, s1, 0x2000
	s_add_i32 s1, s61, s4
	global_load_lds_dwordx4 v142, s[46:47]
	s_add_u32 s46, s46, s18
	s_addc_u32 s47, s47, s19
	s_mov_b32 m0, s1
	s_nop 0
	global_load_lds_dwordx4 v0, s[46:47]
	s_add_i32 m0, s1, 0x2000
	s_nop 0
	global_load_lds_dwordx4 v142, s[46:47]
	s_add_u32 s46, s50, 0x80
	s_addc_u32 s47, s51, 0
	s_mov_b32 m0, s55
	s_nop 0
	global_load_lds_dwordx4 v146, s[46:47]
	s_mov_b32 m0, s56
	s_nop 0
	global_load_lds_dwordx4 v144, s[46:47]
	s_waitcnt vmcnt(8)
	s_waitcnt lgkmcnt(0)
	s_barrier
	s_setprio 1
	s_waitcnt lgkmcnt(0)
	v_mfma_f32_16x16x32_bf16 v[62:65], v[130:133], v[178:181], v[62:65]
	v_mfma_f32_16x16x32_bf16 v[58:61], v[138:141], v[178:181], v[58:61]
	v_mfma_f32_16x16x32_bf16 v[46:49], v[130:133], v[192:195], v[46:49]
	v_mfma_f32_16x16x32_bf16 v[42:45], v[138:141], v[192:195], v[42:45]
	v_mfma_f32_16x16x32_bf16 v[30:33], v[130:133], v[200:203], v[30:33]
	v_mfma_f32_16x16x32_bf16 v[26:29], v[138:141], v[200:203], v[26:29]
	v_mfma_f32_16x16x32_bf16 v[14:17], v[130:133], v[208:211], v[14:17]
	v_mfma_f32_16x16x32_bf16 v[10:13], v[138:141], v[208:211], v[10:13]
	v_mfma_f32_16x16x32_bf16 v[62:65], v[134:137], v[182:185], v[62:65]
	v_mfma_f32_16x16x32_bf16 v[58:61], v[154:157], v[182:185], v[58:61]
	v_mfma_f32_16x16x32_bf16 v[46:49], v[134:137], v[196:199], v[46:49]
	v_mfma_f32_16x16x32_bf16 v[42:45], v[154:157], v[196:199], v[42:45]
	v_mfma_f32_16x16x32_bf16 v[30:33], v[134:137], v[204:207], v[30:33]
	v_mfma_f32_16x16x32_bf16 v[26:29], v[154:157], v[204:207], v[26:29]
	v_mfma_f32_16x16x32_bf16 v[14:17], v[134:137], v[212:215], v[14:17]
	v_mfma_f32_16x16x32_bf16 v[10:13], v[154:157], v[212:215], v[10:13]
	s_setprio 0
	s_setprio 1
	v_mfma_f32_16x16x32_bf16 v[54:57], v[162:165], v[178:181], v[54:57]
	v_mfma_f32_16x16x32_bf16 v[50:53], v[170:173], v[178:181], v[50:53]
	v_mfma_f32_16x16x32_bf16 v[38:41], v[162:165], v[192:195], v[38:41]
	v_mfma_f32_16x16x32_bf16 v[34:37], v[170:173], v[192:195], v[34:37]
	v_mfma_f32_16x16x32_bf16 v[22:25], v[162:165], v[200:203], v[22:25]
	v_mfma_f32_16x16x32_bf16 v[18:21], v[170:173], v[200:203], v[18:21]
	v_mfma_f32_16x16x32_bf16 v[6:9], v[162:165], v[208:211], v[6:9]
	v_mfma_f32_16x16x32_bf16 v[2:5], v[170:173], v[208:211], v[2:5]
	v_mfma_f32_16x16x32_bf16 v[54:57], v[166:169], v[182:185], v[54:57]
	v_mfma_f32_16x16x32_bf16 v[50:53], v[174:177], v[182:185], v[50:53]
	v_mfma_f32_16x16x32_bf16 v[38:41], v[166:169], v[196:199], v[38:41]
	v_mfma_f32_16x16x32_bf16 v[34:37], v[174:177], v[196:199], v[34:37]
	v_mfma_f32_16x16x32_bf16 v[22:25], v[166:169], v[204:207], v[22:25]
	v_mfma_f32_16x16x32_bf16 v[18:21], v[174:177], v[204:207], v[18:21]
	v_mfma_f32_16x16x32_bf16 v[6:9], v[166:169], v[212:215], v[6:9]
	v_mfma_f32_16x16x32_bf16 v[2:5], v[174:177], v[212:215], v[2:5]
	s_setprio 0
	s_barrier
	s_cmp_ge_i32 s60, s57
	s_mov_b64 s[46:47], s[48:49]
	s_mov_b32 s50, s60
	s_cbranch_scc0 .LBB0_450
